# address VALU ops left between phase-closing barriers and the next segment's first ds_read also moved into the preceding MFMA block (12 ops in the five K-loops that still compute DMA addresses on the V
# baseline (speedup 1.0000x reference)
; #define PG8_STAGE(bufoff, gbase, voff) do { _Pragma("unroll") for (int _i = 0; _i < 2; ++_i) \
;         __builtin_amdgcn_global_load_lds((const unsigned*)((const char*)(gbase) + (voff)[_i]), (PG8_LAS unsigned*)(lds + (bufoff) + ldsw + _i * 8192), 16, 0, 0); } while (0)
; #define PG8_LDA(dst, b, h) do { _Pragma("unroll") for (int m = 0; m < 4; ++m) _Pragma("unroll") for (int k = 0; k < 2; ++k) dst[m][k] = *(const PG8_LAS bf16x8*)(lds + PG8_SA(b, h) + aoff + m * 2048 + k * 1024); } while (0)
; #define PG8_LDB(dst, b, h) do { _Pragma("unroll") for (int n = 0; n < 2; ++n) _Pragma("unroll") for (int k = 0; k < 2; ++k) dst[n][k] = *(const PG8_LAS bf16x8*)(lds + PG8_SB(b, h) + boff + n * 2048 + k * 1024); } while (0)
; #define PG8_MMA(ai, bj, At, Bt) do { __builtin_amdgcn_s_setprio(1); _Pragma("unroll") for (int m = 0; m < 4; ++m) _Pragma("unroll") for (int n = 0; n < 2; ++n) _Pragma("unroll") for (int k = 0; k < 2; ++k) \
;         acc[ai][bj][m][n] = __builtin_amdgcn_mfma_f32_16x16x32_bf16(Bt[n][k], At[m][k], acc[ai][bj][m][n], 0, 0, 0); __builtin_amdgcn_s_setprio(0); } while (0)
; #define PG8_WAIT_V(n) asm volatile("s_waitcnt vmcnt(" #n ")" ::: "memory")
; #define PG8_WAIT_L(n) asm volatile("s_waitcnt lgkmcnt(" #n ")" ::: "memory")
; #define PG8_BAR __builtin_amdgcn_s_barrier()
; #define PG8_SCHED __builtin_amdgcn_sched_barrier(0)
; template <class Epi, bool ALIGN_EPI, bool ABLK = false>
; __device__ __forceinline__ void gemm_phase(PG8_LAS unsigned char* lds, const Gemm g, const StaticOrder& S, const Epi& E) {
;     ...
;             const char* a1 = cA + (size_t)(t + 1) * kstepA;
;             const char* a2 = last ? nA : cA + (size_t)(t + 2) * kstepA; const char* b2 = last ? nB : cB + (size_t)(t + 2) * kstepB;
;             const char* a3 = a2 + kstepA; const char* b3 = b2 + kstepB;
;             PG8_LDB(B0, 0, 0); PG8_LDB(B1, 0, 1); PG8_SCHED; PG8_LDA(At, 0, 0); PG8_STAGE(PG8_SA(1, 1), a1 + hstepA, voffA);
;             PG8_WAIT_V(8); PG8_WAIT_L(0); PG8_BAR; PG8_MMA(0, 0, At, B0); PG8_MMA(0, 1, At, B1); PG8_BAR; PG8_SCHED;
;             PG8_LDA(At, 0, 1); PG8_STAGE(PG8_SB(0, 0), b2, voffB); PG8_STAGE(PG8_SB(0, 1), b2 + hstepB, voffB); PG8_STAGE(PG8_SA(0, 0), a2, voffA);
.LBB0_540:
	ds_read_b128 v[98:101], v238
	ds_read_b128 v[110:113], v238 offset:1024
	ds_read_b128 v[122:125], v238 offset:2048
	ds_read_b128 v[126:129], v238 offset:3072
	ds_read_b128 v[134:137], v239
	ds_read_b128 v[142:145], v239 offset:1024
	ds_read_b128 v[146:149], v239 offset:2048
	ds_read_b128 v[150:153], v239 offset:3072
	s_cmp_eq_u32 s78, 40
	s_cselect_b32 s81, s9, s51
	s_cselect_b32 s80, s8, s50
	s_cselect_b32 s53, s49, s55
	s_cselect_b32 s52, s48, s54
	s_movk_i32 s82, 0xc000
	v_lshl_add_u64 v[242:243], s[50:51], 0, v[194:195]
	s_mov_b32 s83, -1
	v_lshl_add_u64 v[244:245], v[242:243], 0, s[82:83]
	s_movk_i32 s82, 0xe000
	s_add_i32 m0, s61, 0xc000
	s_mov_b32 s83, -1
	ds_read_b128 v[154:157], v240
	ds_read_b128 v[166:169], v240 offset:1024
	ds_read_b128 v[170:173], v240 offset:2048
	ds_read_b128 v[174:177], v240 offset:3072
	ds_read_b128 v[178:181], v240 offset:4096
	ds_read_b128 v[182:185], v240 offset:5120
	ds_read_b128 v[186:189], v240 offset:6144
	ds_read_b128 v[190:193], v240 offset:7168
	global_load_lds_dwordx4 v[244:245], off
	v_lshl_add_u64 v[242:243], v[242:243], 0, s[82:83]
	s_add_i32 m0, s61, 0xe000
	s_nop 0
	global_load_lds_dwordx4 v[242:243], off
	s_waitcnt vmcnt(8)
	s_waitcnt lgkmcnt(0)
	s_barrier
	s_setprio 1
	s_waitcnt lgkmcnt(0)
	v_mfma_f32_16x16x32_bf16 v[162:165], v[98:101], v[154:157], v[162:165]
	v_mfma_f32_16x16x32_bf16 v[158:161], v[122:125], v[154:157], v[158:161]
	v_mfma_f32_16x16x32_bf16 v[118:121], v[98:101], v[170:173], v[118:121]
	v_mfma_f32_16x16x32_bf16 v[114:117], v[122:125], v[170:173], v[114:117]
	v_mfma_f32_16x16x32_bf16 v[94:97], v[98:101], v[178:181], v[94:97]
	v_mfma_f32_16x16x32_bf16 v[90:93], v[122:125], v[178:181], v[90:93]
	v_mfma_f32_16x16x32_bf16 v[78:81], v[98:101], v[186:189], v[78:81]
	v_mfma_f32_16x16x32_bf16 v[74:77], v[122:125], v[186:189], v[74:77]
	v_mfma_f32_16x16x32_bf16 v[162:165], v[110:113], v[166:169], v[162:165]
	v_mfma_f32_16x16x32_bf16 v[158:161], v[126:129], v[166:169], v[158:161]
	v_mfma_f32_16x16x32_bf16 v[118:121], v[110:113], v[174:177], v[118:121]
	v_mfma_f32_16x16x32_bf16 v[114:117], v[126:129], v[174:177], v[114:117]
	v_mfma_f32_16x16x32_bf16 v[94:97], v[110:113], v[182:185], v[94:97]
	v_mfma_f32_16x16x32_bf16 v[90:93], v[126:129], v[182:185], v[90:93]
	v_mfma_f32_16x16x32_bf16 v[78:81], v[110:113], v[190:193], v[78:81]
	v_mfma_f32_16x16x32_bf16 v[74:77], v[126:129], v[190:193], v[74:77]
	s_setprio 0
	s_setprio 1
	v_mfma_f32_16x16x32_bf16 v[138:141], v[134:137], v[154:157], v[138:141]
	s_add_i32 s79, s73, s59
	v_mfma_f32_16x16x32_bf16 v[130:133], v[146:149], v[154:157], v[130:133]
	s_mov_b32 m0, s79
	v_mfma_f32_16x16x32_bf16 v[106:109], v[134:137], v[170:173], v[106:109]
	v_mfma_f32_16x16x32_bf16 v[102:105], v[146:149], v[170:173], v[102:105]
	v_mfma_f32_16x16x32_bf16 v[86:89], v[134:137], v[178:181], v[86:89]
	v_mfma_f32_16x16x32_bf16 v[82:85], v[146:149], v[178:181], v[82:85]
	v_mfma_f32_16x16x32_bf16 v[70:73], v[134:137], v[186:189], v[70:73]
	v_mfma_f32_16x16x32_bf16 v[66:69], v[146:149], v[186:189], v[66:69]
	v_mfma_f32_16x16x32_bf16 v[138:141], v[142:145], v[166:169], v[138:141]
	v_mfma_f32_16x16x32_bf16 v[130:133], v[150:153], v[166:169], v[130:133]
	v_mfma_f32_16x16x32_bf16 v[106:109], v[142:145], v[174:177], v[106:109]
	v_lshl_add_u64 v[242:243], s[52:53], 0, v[196:197]
	v_mfma_f32_16x16x32_bf16 v[102:105], v[150:153], v[174:177], v[102:105]
	v_mfma_f32_16x16x32_bf16 v[86:89], v[142:145], v[182:185], v[86:89]
	v_mfma_f32_16x16x32_bf16 v[82:85], v[150:153], v[182:185], v[82:85]
	v_mfma_f32_16x16x32_bf16 v[70:73], v[142:145], v[190:193], v[70:73]
	v_mfma_f32_16x16x32_bf16 v[66:69], v[150:153], v[190:193], v[66:69]
	s_setprio 0
	s_barrier
	ds_read_b128 v[154:157], v240 offset:16384
	ds_read_b128 v[166:169], v240 offset:17408
	ds_read_b128 v[170:173], v240 offset:18432
	ds_read_b128 v[174:177], v240 offset:19456
	ds_read_b128 v[178:181], v240 offset:20480
	ds_read_b128 v[182:185], v240 offset:21504
	ds_read_b128 v[186:189], v240 offset:22528
	ds_read_b128 v[190:193], v240 offset:23552
	global_load_lds_dwordx4 v[242:243], off
	s_add_i32 m0, s79, 0x2000
	s_add_u32 s82, s52, 0xb0000
	v_lshl_add_u64 v[244:245], s[52:53], 0, v[198:199]
	s_addc_u32 s83, s53, 0
	s_add_i32 s79, s74, s59
	global_load_lds_dwordx4 v[244:245], off
	v_lshl_add_u64 v[246:247], s[82:83], 0, v[196:197]
	s_mov_b32 m0, s79
	s_nop 0
	global_load_lds_dwordx4 v[246:247], off
	v_lshl_add_u64 v[246:247], s[82:83], 0, v[198:199]
	s_add_i32 m0, s79, 0x2000
	s_nop 0
	global_load_lds_dwordx4 v[246:247], off
	v_lshl_add_u64 v[246:247], s[80:81], 0, v[194:195]
	s_mov_b32 m0, s61
	v_lshl_add_u64 v[248:249], v[246:247], 0, s[10:11]
	global_load_lds_dwordx4 v[246:247], off
	s_mov_b32 m0, s62
	s_nop 0
	global_load_lds_dwordx4 v[248:249], off
	s_waitcnt vmcnt(8)
	s_waitcnt lgkmcnt(0)
	s_barrier
; #define PG8_STAGE(bufoff, gbase, voff) do { _Pragma("unroll") for (int _i = 0; _i < 2; ++_i) \
;         __builtin_amdgcn_global_load_lds((const unsigned*)((const char*)(gbase) + (voff)[_i]), (PG8_LAS unsigned*)(lds + (bufoff) + ldsw + _i * 8192), 16, 0, 0); } while (0)
; #define PG8_LDA(dst, b, h) do { _Pragma("unroll") for (int m = 0; m < 4; ++m) _Pragma("unroll") for (int k = 0; k < 2; ++k) dst[m][k] = *(const PG8_LAS bf16x8*)(lds + PG8_SA(b, h) + aoff + m * 2048 + k * 1024); } while (0)
; #define PG8_LDB(dst, b, h) do { _Pragma("unroll") for (int n = 0; n < 2; ++n) _Pragma("unroll") for (int k = 0; k < 2; ++k) dst[n][k] = *(const PG8_LAS bf16x8*)(lds + PG8_SB(b, h) + boff + n * 2048 + k * 1024); } while (0)
; #define PG8_MMA(ai, bj, At, Bt) do { __builtin_amdgcn_s_setprio(1); _Pragma("unroll") for (int m = 0; m < 4; ++m) _Pragma("unroll") for (int n = 0; n < 2; ++n) _Pragma("unroll") for (int k = 0; k < 2; ++k) \
;         acc[ai][bj][m][n] = __builtin_amdgcn_mfma_f32_16x16x32_bf16(Bt[n][k], At[m][k], acc[ai][bj][m][n], 0, 0, 0); __builtin_amdgcn_s_setprio(0); } while (0)
; #define PG8_WAIT_V(n) asm volatile("s_waitcnt vmcnt(" #n ")" ::: "memory")
; #define PG8_WAIT_L(n) asm volatile("s_waitcnt lgkmcnt(" #n ")" ::: "memory")
; #define PG8_BAR __builtin_amdgcn_s_barrier()
; #define PG8_SCHED __builtin_amdgcn_sched_barrier(0)
; template <class Epi, bool ALIGN_EPI, bool ABLK = false>
; __device__ __forceinline__ void gemm_phase(PG8_LAS unsigned char* lds, const Gemm g, const StaticOrder& S, const Epi& E) {
;     ...
;             PG8_WAIT_V(8); PG8_WAIT_L(0); PG8_BAR; PG8_MMA(1, 0, At, B0); PG8_MMA(1, 1, At, B1); PG8_BAR; PG8_SCHED;
;             PG8_LDB(B0, 1, 0); PG8_LDB(B1, 1, 1); PG8_SCHED; PG8_LDA(At, 1, 0); PG8_STAGE(PG8_SA(0, 1), a2 + hstepA, voffA);
;             PG8_WAIT_V(8); PG8_WAIT_L(0); PG8_BAR; PG8_MMA(0, 0, At, B0); PG8_MMA(0, 1, At, B1); PG8_BAR; PG8_SCHED;
	s_setprio 1
	s_waitcnt lgkmcnt(0)
	v_mfma_f32_16x16x32_bf16 v[62:65], v[98:101], v[154:157], v[62:65]
	v_mfma_f32_16x16x32_bf16 v[58:61], v[122:125], v[154:157], v[58:61]
	v_mfma_f32_16x16x32_bf16 v[46:49], v[98:101], v[170:173], v[46:49]
	v_mfma_f32_16x16x32_bf16 v[42:45], v[122:125], v[170:173], v[42:45]
	v_mfma_f32_16x16x32_bf16 v[30:33], v[98:101], v[178:181], v[30:33]
	v_mfma_f32_16x16x32_bf16 v[26:29], v[122:125], v[178:181], v[26:29]
	v_mfma_f32_16x16x32_bf16 v[14:17], v[98:101], v[186:189], v[14:17]
	v_mfma_f32_16x16x32_bf16 v[10:13], v[122:125], v[186:189], v[10:13]
	v_mfma_f32_16x16x32_bf16 v[62:65], v[110:113], v[166:169], v[62:65]
	v_mfma_f32_16x16x32_bf16 v[58:61], v[126:129], v[166:169], v[58:61]
	v_mfma_f32_16x16x32_bf16 v[46:49], v[110:113], v[174:177], v[46:49]
	v_mfma_f32_16x16x32_bf16 v[42:45], v[126:129], v[174:177], v[42:45]
	v_mfma_f32_16x16x32_bf16 v[30:33], v[110:113], v[182:185], v[30:33]
	v_mfma_f32_16x16x32_bf16 v[26:29], v[126:129], v[182:185], v[26:29]
	v_mfma_f32_16x16x32_bf16 v[14:17], v[110:113], v[190:193], v[14:17]
	v_mfma_f32_16x16x32_bf16 v[10:13], v[126:129], v[190:193], v[10:13]
	s_setprio 0
	s_setprio 1
	v_mfma_f32_16x16x32_bf16 v[54:57], v[134:137], v[154:157], v[54:57]
	s_add_i32 s79, 0, 0x18000
	v_mfma_f32_16x16x32_bf16 v[50:53], v[146:149], v[154:157], v[50:53]
	s_add_i32 s80, 0, 0x1c000
	v_mfma_f32_16x16x32_bf16 v[38:41], v[134:137], v[170:173], v[38:41]
	v_mfma_f32_16x16x32_bf16 v[34:37], v[146:149], v[170:173], v[34:37]
	v_mfma_f32_16x16x32_bf16 v[22:25], v[134:137], v[178:181], v[22:25]
	v_mfma_f32_16x16x32_bf16 v[18:21], v[146:149], v[178:181], v[18:21]
	v_mfma_f32_16x16x32_bf16 v[6:9], v[134:137], v[186:189], v[6:9]
	v_mfma_f32_16x16x32_bf16 v[2:5], v[146:149], v[186:189], v[2:5]
	v_mfma_f32_16x16x32_bf16 v[54:57], v[142:145], v[166:169], v[54:57]
	v_mfma_f32_16x16x32_bf16 v[50:53], v[150:153], v[166:169], v[50:53]
	v_mfma_f32_16x16x32_bf16 v[38:41], v[142:145], v[174:177], v[38:41]
	v_mfma_f32_16x16x32_bf16 v[34:37], v[150:153], v[174:177], v[34:37]
	v_mfma_f32_16x16x32_bf16 v[22:25], v[142:145], v[182:185], v[22:25]
	v_mfma_f32_16x16x32_bf16 v[18:21], v[150:153], v[182:185], v[18:21]
	v_mfma_f32_16x16x32_bf16 v[6:9], v[142:145], v[190:193], v[6:9]
	v_mfma_f32_16x16x32_bf16 v[2:5], v[150:153], v[190:193], v[2:5]
	s_setprio 0
	s_barrier
	v_add_u32_e32 v126, s79, v230
	v_add_u32_e32 v150, s80, v230
	ds_read_b128 v[98:101], v126
	ds_read_b128 v[110:113], v126 offset:1024
	ds_read_b128 v[122:125], v126 offset:2048
	ds_read_b128 v[126:129], v126 offset:3072
	ds_read_b128 v[134:137], v150
	ds_read_b128 v[142:145], v150 offset:1024
	ds_read_b128 v[146:149], v150 offset:2048
	ds_read_b128 v[150:153], v150 offset:3072
	s_mov_b32 m0, s63
	v_lshl_add_u64 v[248:249], v[246:247], 0, s[12:13]
	ds_read_b128 v[154:157], v240 offset:32768
	ds_read_b128 v[166:169], v240 offset:33792
	ds_read_b128 v[170:173], v240 offset:34816
	ds_read_b128 v[174:177], v240 offset:35840
	ds_read_b128 v[178:181], v240 offset:36864
	ds_read_b128 v[182:185], v240 offset:37888
	ds_read_b128 v[186:189], v240 offset:38912
	ds_read_b128 v[190:193], v240 offset:39936
	global_load_lds_dwordx4 v[248:249], off
	v_lshl_add_u64 v[248:249], v[246:247], 0, s[24:25]
	s_mov_b32 m0, s64
	s_nop 0
	global_load_lds_dwordx4 v[248:249], off
	s_waitcnt vmcnt(8)
	s_waitcnt lgkmcnt(0)
	s_barrier
	s_setprio 1
	s_waitcnt lgkmcnt(0)
	v_mfma_f32_16x16x32_bf16 v[162:165], v[98:101], v[154:157], v[162:165]
	v_mfma_f32_16x16x32_bf16 v[158:161], v[122:125], v[154:157], v[158:161]
	v_mfma_f32_16x16x32_bf16 v[118:121], v[98:101], v[170:173], v[118:121]
	v_mfma_f32_16x16x32_bf16 v[114:117], v[122:125], v[170:173], v[114:117]
	v_mfma_f32_16x16x32_bf16 v[94:97], v[98:101], v[178:181], v[94:97]
	v_mfma_f32_16x16x32_bf16 v[90:93], v[122:125], v[178:181], v[90:93]
	v_mfma_f32_16x16x32_bf16 v[78:81], v[98:101], v[186:189], v[78:81]
	v_mfma_f32_16x16x32_bf16 v[74:77], v[122:125], v[186:189], v[74:77]
	v_mfma_f32_16x16x32_bf16 v[162:165], v[110:113], v[166:169], v[162:165]
	v_mfma_f32_16x16x32_bf16 v[158:161], v[126:129], v[166:169], v[158:161]
	v_mfma_f32_16x16x32_bf16 v[118:121], v[110:113], v[174:177], v[118:121]
	v_mfma_f32_16x16x32_bf16 v[114:117], v[126:129], v[174:177], v[114:117]
	v_mfma_f32_16x16x32_bf16 v[94:97], v[110:113], v[182:185], v[94:97]
	v_mfma_f32_16x16x32_bf16 v[90:93], v[126:129], v[182:185], v[90:93]
	v_mfma_f32_16x16x32_bf16 v[78:81], v[110:113], v[190:193], v[78:81]
	v_mfma_f32_16x16x32_bf16 v[74:77], v[126:129], v[190:193], v[74:77]
	s_setprio 0
	s_setprio 1
	v_mfma_f32_16x16x32_bf16 v[138:141], v[134:137], v[154:157], v[138:141]
	s_add_i32 s79, s79, s59
	v_mfma_f32_16x16x32_bf16 v[130:133], v[146:149], v[154:157], v[130:133]
	s_mov_b32 m0, s79
	v_mfma_f32_16x16x32_bf16 v[106:109], v[134:137], v[170:173], v[106:109]
	v_mfma_f32_16x16x32_bf16 v[102:105], v[146:149], v[170:173], v[102:105]
	v_mfma_f32_16x16x32_bf16 v[86:89], v[134:137], v[178:181], v[86:89]
	v_mfma_f32_16x16x32_bf16 v[82:85], v[146:149], v[178:181], v[82:85]
	v_mfma_f32_16x16x32_bf16 v[70:73], v[134:137], v[186:189], v[70:73]
	v_mfma_f32_16x16x32_bf16 v[66:69], v[146:149], v[186:189], v[66:69]
	v_mfma_f32_16x16x32_bf16 v[138:141], v[142:145], v[166:169], v[138:141]
	v_mfma_f32_16x16x32_bf16 v[130:133], v[150:153], v[166:169], v[130:133]
	v_mfma_f32_16x16x32_bf16 v[106:109], v[142:145], v[174:177], v[106:109]
	v_lshl_add_u64 v[242:243], v[242:243], 0, s[34:35]
	v_mfma_f32_16x16x32_bf16 v[102:105], v[150:153], v[174:177], v[102:105]
	v_mfma_f32_16x16x32_bf16 v[86:89], v[142:145], v[182:185], v[86:89]
	v_mfma_f32_16x16x32_bf16 v[82:85], v[150:153], v[182:185], v[82:85]
	v_mfma_f32_16x16x32_bf16 v[70:73], v[142:145], v[190:193], v[70:73]
	v_mfma_f32_16x16x32_bf16 v[66:69], v[150:153], v[190:193], v[66:69]
	s_setprio 0
	s_barrier
; #define PG8_STAGE(bufoff, gbase, voff) do { _Pragma("unroll") for (int _i = 0; _i < 2; ++_i) \
;         __builtin_amdgcn_global_load_lds((const unsigned*)((const char*)(gbase) + (voff)[_i]), (PG8_LAS unsigned*)(lds + (bufoff) + ldsw + _i * 8192), 16, 0, 0); } while (0)
; #define PG8_LDA(dst, b, h) do { _Pragma("unroll") for (int m = 0; m < 4; ++m) _Pragma("unroll") for (int k = 0; k < 2; ++k) dst[m][k] = *(const PG8_LAS bf16x8*)(lds + PG8_SA(b, h) + aoff + m * 2048 + k * 1024); } while (0)
; #define PG8_MMA(ai, bj, At, Bt) do { __builtin_amdgcn_s_setprio(1); _Pragma("unroll") for (int m = 0; m < 4; ++m) _Pragma("unroll") for (int n = 0; n < 2; ++n) _Pragma("unroll") for (int k = 0; k < 2; ++k) \
;         acc[ai][bj][m][n] = __builtin_amdgcn_mfma_f32_16x16x32_bf16(Bt[n][k], At[m][k], acc[ai][bj][m][n], 0, 0, 0); __builtin_amdgcn_s_setprio(0); } while (0)
; #define PG8_WAIT_V(n) asm volatile("s_waitcnt vmcnt(" #n ")" ::: "memory")
; #define PG8_WAIT_L(n) asm volatile("s_waitcnt lgkmcnt(" #n ")" ::: "memory")
; #define PG8_BAR __builtin_amdgcn_s_barrier()
; #define PG8_SCHED __builtin_amdgcn_sched_barrier(0)
; template <class Epi, bool ALIGN_EPI, bool ABLK = false>
; __device__ __forceinline__ void gemm_phase(PG8_LAS unsigned char* lds, const Gemm g, const StaticOrder& S, const Epi& E) {
;     ...
;             PG8_LDA(At, 1, 1); PG8_STAGE(PG8_SB(1, 0), b3, voffB); PG8_STAGE(PG8_SB(1, 1), b3 + hstepB, voffB); PG8_STAGE(PG8_SA(1, 0), a3, voffA);
;             PG8_WAIT_V(8); PG8_WAIT_L(0); PG8_BAR; PG8_MMA(1, 0, At, B0); PG8_MMA(1, 1, At, B1); PG8_BAR; PG8_SCHED;
;         }
	ds_read_b128 v[154:157], v240 offset:49152
	ds_read_b128 v[166:169], v240 offset:50176
	ds_read_b128 v[170:173], v240 offset:51200
	ds_read_b128 v[174:177], v240 offset:52224
	ds_read_b128 v[178:181], v240 offset:53248
	ds_read_b128 v[182:185], v240 offset:54272
	ds_read_b128 v[186:189], v240 offset:55296
	ds_read_b128 v[190:193], v240 offset:56320
	global_load_lds_dwordx4 v[242:243], off
	s_add_i32 m0, s79, 0x2000
	s_add_u32 s52, s52, 0xb0080
	v_lshl_add_u64 v[242:243], v[244:245], 0, s[34:35]
	s_addc_u32 s53, s53, 0
	s_add_i32 s79, s80, s59
	global_load_lds_dwordx4 v[242:243], off
	v_lshl_add_u64 v[242:243], s[52:53], 0, v[196:197]
	s_mov_b32 m0, s79
	s_nop 0
	global_load_lds_dwordx4 v[242:243], off
	v_lshl_add_u64 v[242:243], s[52:53], 0, v[198:199]
	s_add_i32 m0, s79, 0x2000
	s_nop 0
	global_load_lds_dwordx4 v[242:243], off
	v_lshl_add_u64 v[242:243], v[246:247], 0, s[36:37]
	s_mov_b32 m0, s67
	s_nop 0
	global_load_lds_dwordx4 v[242:243], off
	v_lshl_add_u64 v[242:243], v[246:247], 0, s[38:39]
	s_mov_b32 m0, s68
	s_nop 0
	global_load_lds_dwordx4 v[242:243], off
	s_waitcnt vmcnt(8)
	s_waitcnt lgkmcnt(0)
	s_barrier
	s_setprio 1
	s_waitcnt lgkmcnt(0)
	v_mfma_f32_16x16x32_bf16 v[62:65], v[98:101], v[154:157], v[62:65]
	v_mfma_f32_16x16x32_bf16 v[58:61], v[122:125], v[154:157], v[58:61]
	v_mfma_f32_16x16x32_bf16 v[46:49], v[98:101], v[170:173], v[46:49]
	v_mfma_f32_16x16x32_bf16 v[42:45], v[122:125], v[170:173], v[42:45]
	v_mfma_f32_16x16x32_bf16 v[30:33], v[98:101], v[178:181], v[30:33]
	v_mfma_f32_16x16x32_bf16 v[26:29], v[122:125], v[178:181], v[26:29]
	v_mfma_f32_16x16x32_bf16 v[14:17], v[98:101], v[186:189], v[14:17]
	v_mfma_f32_16x16x32_bf16 v[10:13], v[122:125], v[186:189], v[10:13]
	v_mfma_f32_16x16x32_bf16 v[62:65], v[110:113], v[166:169], v[62:65]
	v_mfma_f32_16x16x32_bf16 v[58:61], v[126:129], v[166:169], v[58:61]
	v_mfma_f32_16x16x32_bf16 v[46:49], v[110:113], v[174:177], v[46:49]
	v_mfma_f32_16x16x32_bf16 v[42:45], v[126:129], v[174:177], v[42:45]
	v_mfma_f32_16x16x32_bf16 v[30:33], v[110:113], v[182:185], v[30:33]
	v_mfma_f32_16x16x32_bf16 v[26:29], v[126:129], v[182:185], v[26:29]
	v_mfma_f32_16x16x32_bf16 v[14:17], v[110:113], v[190:193], v[14:17]
	v_mfma_f32_16x16x32_bf16 v[10:13], v[126:129], v[190:193], v[10:13]
	s_setprio 0
	s_setprio 1
	v_mfma_f32_16x16x32_bf16 v[54:57], v[134:137], v[154:157], v[54:57]
	s_add_i32 s78, s78, 2
	v_mfma_f32_16x16x32_bf16 v[50:53], v[146:149], v[154:157], v[50:53]
	s_add_u32 s54, s54, 0x100
	v_mfma_f32_16x16x32_bf16 v[38:41], v[134:137], v[170:173], v[38:41]
	s_addc_u32 s55, s55, 0
	v_mfma_f32_16x16x32_bf16 v[34:37], v[146:149], v[170:173], v[34:37]
	s_add_u32 s50, s50, 0x10000
	v_mfma_f32_16x16x32_bf16 v[22:25], v[134:137], v[178:181], v[22:25]
	s_addc_u32 s51, s51, 0
	v_mfma_f32_16x16x32_bf16 v[18:21], v[146:149], v[178:181], v[18:21]
	s_cmp_gt_u32 s78, 41
	v_mfma_f32_16x16x32_bf16 v[6:9], v[134:137], v[186:189], v[6:9]
	v_mfma_f32_16x16x32_bf16 v[2:5], v[146:149], v[186:189], v[2:5]
	v_mfma_f32_16x16x32_bf16 v[54:57], v[142:145], v[166:169], v[54:57]
	v_mfma_f32_16x16x32_bf16 v[50:53], v[150:153], v[166:169], v[50:53]
	v_mfma_f32_16x16x32_bf16 v[38:41], v[142:145], v[174:177], v[38:41]
	v_mfma_f32_16x16x32_bf16 v[34:37], v[150:153], v[174:177], v[34:37]
	v_mfma_f32_16x16x32_bf16 v[22:25], v[142:145], v[182:185], v[22:25]
	v_mfma_f32_16x16x32_bf16 v[18:21], v[150:153], v[182:185], v[18:21]
	v_mfma_f32_16x16x32_bf16 v[6:9], v[142:145], v[190:193], v[6:9]
	v_mfma_f32_16x16x32_bf16 v[2:5], v[150:153], v[190:193], v[2:5]
	s_setprio 0
	s_barrier
	s_cbranch_scc0 .LBB0_540
	s_and_b64 vcc, exec, s[40:41]
	s_cbranch_vccz .LBB0_543
	s_barrier

; #define PG8_STAGE(bufoff, gbase, voff) do { _Pragma("unroll") for (int _i = 0; _i < 2; ++_i) \
;         __builtin_amdgcn_global_load_lds((const unsigned*)((const char*)(gbase) + (voff)[_i]), (PG8_LAS unsigned*)(lds + (bufoff) + ldsw + _i * 8192), 16, 0, 0); } while (0)
; #define PG8_LDA(dst, b, h) do { _Pragma("unroll") for (int m = 0; m < 4; ++m) _Pragma("unroll") for (int k = 0; k < 2; ++k) dst[m][k] = *(const PG8_LAS bf16x8*)(lds + PG8_SA(b, h) + aoff + m * 2048 + k * 1024); } while (0)
; #define PG8_LDB(dst, b, h) do { _Pragma("unroll") for (int n = 0; n < 2; ++n) _Pragma("unroll") for (int k = 0; k < 2; ++k) dst[n][k] = *(const PG8_LAS bf16x8*)(lds + PG8_SB(b, h) + boff + n * 2048 + k * 1024); } while (0)
; #define PG8_MMA(ai, bj, At, Bt) do { __builtin_amdgcn_s_setprio(1); _Pragma("unroll") for (int m = 0; m < 4; ++m) _Pragma("unroll") for (int n = 0; n < 2; ++n) _Pragma("unroll") for (int k = 0; k < 2; ++k) \
;         acc[ai][bj][m][n] = __builtin_amdgcn_mfma_f32_16x16x32_bf16(Bt[n][k], At[m][k], acc[ai][bj][m][n], 0, 0, 0); __builtin_amdgcn_s_setprio(0); } while (0)
; #define PG8_WAIT_V(n) asm volatile("s_waitcnt vmcnt(" #n ")" ::: "memory")
; #define PG8_WAIT_L(n) asm volatile("s_waitcnt lgkmcnt(" #n ")" ::: "memory")
; #define PG8_BAR __builtin_amdgcn_s_barrier()
; #define PG8_SCHED __builtin_amdgcn_sched_barrier(0)
; template <class Epi, bool ALIGN_EPI, bool ABLK = false>
; __device__ __forceinline__ void gemm_phase(PG8_LAS unsigned char* lds, const Gemm g, const StaticOrder& S, const Epi& E) {
;     ...
;             const char* a1 = cA + (size_t)(t + 1) * kstepA;
;             const char* a2 = last ? nA : cA + (size_t)(t + 2) * kstepA; const char* b2 = last ? nB : cB + (size_t)(t + 2) * kstepB;
;             const char* a3 = a2 + kstepA; const char* b3 = b2 + kstepB;
;             PG8_LDB(B0, 0, 0); PG8_LDB(B1, 0, 1); PG8_SCHED; PG8_LDA(At, 0, 0); PG8_STAGE(PG8_SA(1, 1), a1 + hstepA, voffA);
;             PG8_WAIT_V(8); PG8_WAIT_L(0); PG8_BAR; PG8_MMA(0, 0, At, B0); PG8_MMA(0, 1, At, B1); PG8_BAR; PG8_SCHED;
;             PG8_LDA(At, 0, 1); PG8_STAGE(PG8_SB(0, 0), b2, voffB); PG8_STAGE(PG8_SB(0, 1), b2 + hstepB, voffB); PG8_STAGE(PG8_SA(0, 0), a2, voffA);
.LBB0_1983:
	v_add_u32_e32 v136, s71, v179
	ds_read_b128 v[132:135], v136
	ds_read_b128 v[184:187], v136 offset:1024
	ds_read_b128 v[188:191], v136 offset:2048
	ds_read_b128 v[192:195], v136 offset:3072
	v_add_u32_e32 v136, s72, v179
	ds_read_b128 v[196:199], v136
	ds_read_b128 v[200:203], v136 offset:1024
	ds_read_b128 v[204:207], v136 offset:2048
	ds_read_b128 v[208:211], v136 offset:3072
	s_add_u32 s62, s26, s60
	s_addc_u32 s63, s27, s61
	s_cmp_eq_u32 s79, 12
	s_cselect_b32 s81, s55, s63
	s_cselect_b32 s80, s75, s62
	s_cselect_b32 s63, s53, s78
	s_cselect_b32 s62, s76, s77
	v_lshl_add_u64 v[136:137], s[26:27], 0, v[130:131]
	v_lshl_add_u64 v[244:245], v[136:137], 0, s[40:41]
	s_add_i32 m0, s23, 0xc000
	ds_read_b128 v[212:215], v182
	ds_read_b128 v[216:219], v182 offset:1024
	ds_read_b128 v[220:223], v182 offset:2048
	ds_read_b128 v[224:227], v182 offset:3072
	ds_read_b128 v[228:231], v182 offset:4096
	ds_read_b128 v[232:235], v182 offset:5120
	ds_read_b128 v[236:239], v182 offset:6144
	ds_read_b128 v[240:243], v182 offset:7168
	global_load_lds_dwordx4 v[244:245], off
	v_lshl_add_u64 v[136:137], v[136:137], 0, s[42:43]
	s_add_i32 m0, s23, 0xe000
	s_nop 0
	global_load_lds_dwordx4 v[136:137], off
	s_waitcnt vmcnt(8)
	s_waitcnt lgkmcnt(0)
	s_barrier
	s_setprio 1
	s_waitcnt lgkmcnt(0)
	v_mfma_f32_16x16x32_bf16 v[126:129], v[132:135], v[212:215], v[126:129]
	v_mfma_f32_16x16x32_bf16 v[122:125], v[188:191], v[212:215], v[122:125]
	v_mfma_f32_16x16x32_bf16 v[118:121], v[132:135], v[220:223], v[118:121]
	v_mfma_f32_16x16x32_bf16 v[114:117], v[188:191], v[220:223], v[114:117]
	v_mfma_f32_16x16x32_bf16 v[110:113], v[132:135], v[228:231], v[110:113]
	v_mfma_f32_16x16x32_bf16 v[106:109], v[188:191], v[228:231], v[106:109]
	v_mfma_f32_16x16x32_bf16 v[102:105], v[132:135], v[236:239], v[102:105]
	v_mfma_f32_16x16x32_bf16 v[98:101], v[188:191], v[236:239], v[98:101]
	v_mfma_f32_16x16x32_bf16 v[126:129], v[184:187], v[216:219], v[126:129]
	v_mfma_f32_16x16x32_bf16 v[122:125], v[192:195], v[216:219], v[122:125]
	v_mfma_f32_16x16x32_bf16 v[118:121], v[184:187], v[224:227], v[118:121]
	v_mfma_f32_16x16x32_bf16 v[114:117], v[192:195], v[224:227], v[114:117]
	v_mfma_f32_16x16x32_bf16 v[110:113], v[184:187], v[232:235], v[110:113]
	v_mfma_f32_16x16x32_bf16 v[106:109], v[192:195], v[232:235], v[106:109]
	v_mfma_f32_16x16x32_bf16 v[102:105], v[184:187], v[240:243], v[102:105]
	v_mfma_f32_16x16x32_bf16 v[98:101], v[192:195], v[240:243], v[98:101]
	s_setprio 0
	s_setprio 1
	v_mfma_f32_16x16x32_bf16 v[94:97], v[196:199], v[212:215], v[94:97]
	s_add_i32 s82, s71, s21
	v_mfma_f32_16x16x32_bf16 v[90:93], v[204:207], v[212:215], v[90:93]
	s_mov_b32 m0, s82
	v_mfma_f32_16x16x32_bf16 v[86:89], v[196:199], v[220:223], v[86:89]
	v_mfma_f32_16x16x32_bf16 v[82:85], v[204:207], v[220:223], v[82:85]
	v_mfma_f32_16x16x32_bf16 v[78:81], v[196:199], v[228:231], v[78:81]
	v_mfma_f32_16x16x32_bf16 v[74:77], v[204:207], v[228:231], v[74:77]
	v_mfma_f32_16x16x32_bf16 v[70:73], v[196:199], v[236:239], v[70:73]
	v_mfma_f32_16x16x32_bf16 v[66:69], v[204:207], v[236:239], v[66:69]
	v_mfma_f32_16x16x32_bf16 v[94:97], v[200:203], v[216:219], v[94:97]
	v_mfma_f32_16x16x32_bf16 v[90:93], v[208:211], v[216:219], v[90:93]
	v_mfma_f32_16x16x32_bf16 v[86:89], v[200:203], v[224:227], v[86:89]
	v_lshl_add_u64 v[136:137], s[62:63], 0, v[140:141]
	v_mfma_f32_16x16x32_bf16 v[82:85], v[208:211], v[224:227], v[82:85]
	v_mfma_f32_16x16x32_bf16 v[78:81], v[200:203], v[232:235], v[78:81]
	v_mfma_f32_16x16x32_bf16 v[74:77], v[208:211], v[232:235], v[74:77]
	v_mfma_f32_16x16x32_bf16 v[70:73], v[200:203], v[240:243], v[70:73]
	v_mfma_f32_16x16x32_bf16 v[66:69], v[208:211], v[240:243], v[66:69]
	s_setprio 0
	s_barrier
	ds_read_b128 v[212:215], v182 offset:16384
	ds_read_b128 v[216:219], v182 offset:17408
	ds_read_b128 v[220:223], v182 offset:18432
	ds_read_b128 v[224:227], v182 offset:19456
	ds_read_b128 v[228:231], v182 offset:20480
	ds_read_b128 v[232:235], v182 offset:21504
	ds_read_b128 v[236:239], v182 offset:22528
	ds_read_b128 v[240:243], v182 offset:23552
	global_load_lds_dwordx4 v[136:137], off
	s_add_i32 m0, s82, 0x2000
	s_add_u32 s82, s62, 0x40000
	v_lshl_add_u64 v[244:245], s[62:63], 0, v[142:143]
	s_addc_u32 s83, s63, 0
	s_add_i32 s84, s72, s21
	global_load_lds_dwordx4 v[244:245], off
	v_lshl_add_u64 v[246:247], s[82:83], 0, v[140:141]
	s_mov_b32 m0, s84
	s_nop 0
	global_load_lds_dwordx4 v[246:247], off
	v_lshl_add_u64 v[246:247], s[82:83], 0, v[142:143]
	s_add_i32 m0, s84, 0x2000
	s_nop 0
	global_load_lds_dwordx4 v[246:247], off
	v_lshl_add_u64 v[246:247], s[80:81], 0, v[138:139]
	s_mov_b32 m0, s23
	v_lshl_add_u64 v[248:249], v[246:247], 0, s[44:45]
	global_load_lds_dwordx4 v[246:247], off
	s_mov_b32 m0, s33
	s_nop 0
	global_load_lds_dwordx4 v[248:249], off
	s_waitcnt vmcnt(8)
	s_waitcnt lgkmcnt(0)
	s_barrier
; #define PG8_STAGE(bufoff, gbase, voff) do { _Pragma("unroll") for (int _i = 0; _i < 2; ++_i) \
;         __builtin_amdgcn_global_load_lds((const unsigned*)((const char*)(gbase) + (voff)[_i]), (PG8_LAS unsigned*)(lds + (bufoff) + ldsw + _i * 8192), 16, 0, 0); } while (0)
; #define PG8_LDA(dst, b, h) do { _Pragma("unroll") for (int m = 0; m < 4; ++m) _Pragma("unroll") for (int k = 0; k < 2; ++k) dst[m][k] = *(const PG8_LAS bf16x8*)(lds + PG8_SA(b, h) + aoff + m * 2048 + k * 1024); } while (0)
; #define PG8_LDB(dst, b, h) do { _Pragma("unroll") for (int n = 0; n < 2; ++n) _Pragma("unroll") for (int k = 0; k < 2; ++k) dst[n][k] = *(const PG8_LAS bf16x8*)(lds + PG8_SB(b, h) + boff + n * 2048 + k * 1024); } while (0)
; #define PG8_MMA(ai, bj, At, Bt) do { __builtin_amdgcn_s_setprio(1); _Pragma("unroll") for (int m = 0; m < 4; ++m) _Pragma("unroll") for (int n = 0; n < 2; ++n) _Pragma("unroll") for (int k = 0; k < 2; ++k) \
;         acc[ai][bj][m][n] = __builtin_amdgcn_mfma_f32_16x16x32_bf16(Bt[n][k], At[m][k], acc[ai][bj][m][n], 0, 0, 0); __builtin_amdgcn_s_setprio(0); } while (0)
; #define PG8_WAIT_V(n) asm volatile("s_waitcnt vmcnt(" #n ")" ::: "memory")
; #define PG8_WAIT_L(n) asm volatile("s_waitcnt lgkmcnt(" #n ")" ::: "memory")
; #define PG8_BAR __builtin_amdgcn_s_barrier()
; #define PG8_SCHED __builtin_amdgcn_sched_barrier(0)
; template <class Epi, bool ALIGN_EPI, bool ABLK = false>
; __device__ __forceinline__ void gemm_phase(PG8_LAS unsigned char* lds, const Gemm g, const StaticOrder& S, const Epi& E) {
;     ...
;             PG8_WAIT_V(8); PG8_WAIT_L(0); PG8_BAR; PG8_MMA(1, 0, At, B0); PG8_MMA(1, 1, At, B1); PG8_BAR; PG8_SCHED;
;             PG8_LDB(B0, 1, 0); PG8_LDB(B1, 1, 1); PG8_SCHED; PG8_LDA(At, 1, 0); PG8_STAGE(PG8_SA(0, 1), a2 + hstepA, voffA);
;             PG8_WAIT_V(8); PG8_WAIT_L(0); PG8_BAR; PG8_MMA(0, 0, At, B0); PG8_MMA(0, 1, At, B1); PG8_BAR; PG8_SCHED;
	s_setprio 1
	s_waitcnt lgkmcnt(0)
	v_mfma_f32_16x16x32_bf16 v[62:65], v[132:135], v[212:215], v[62:65]
	v_mfma_f32_16x16x32_bf16 v[58:61], v[188:191], v[212:215], v[58:61]
	v_mfma_f32_16x16x32_bf16 v[54:57], v[132:135], v[220:223], v[54:57]
	v_mfma_f32_16x16x32_bf16 v[50:53], v[188:191], v[220:223], v[50:53]
	v_mfma_f32_16x16x32_bf16 v[46:49], v[132:135], v[228:231], v[46:49]
	v_mfma_f32_16x16x32_bf16 v[42:45], v[188:191], v[228:231], v[42:45]
	v_mfma_f32_16x16x32_bf16 v[38:41], v[132:135], v[236:239], v[38:41]
	v_mfma_f32_16x16x32_bf16 v[34:37], v[188:191], v[236:239], v[34:37]
	v_mfma_f32_16x16x32_bf16 v[62:65], v[184:187], v[216:219], v[62:65]
	v_mfma_f32_16x16x32_bf16 v[58:61], v[192:195], v[216:219], v[58:61]
	v_mfma_f32_16x16x32_bf16 v[54:57], v[184:187], v[224:227], v[54:57]
	v_mfma_f32_16x16x32_bf16 v[50:53], v[192:195], v[224:227], v[50:53]
	v_mfma_f32_16x16x32_bf16 v[46:49], v[184:187], v[232:235], v[46:49]
	v_mfma_f32_16x16x32_bf16 v[42:45], v[192:195], v[232:235], v[42:45]
	v_mfma_f32_16x16x32_bf16 v[38:41], v[184:187], v[240:243], v[38:41]
	v_mfma_f32_16x16x32_bf16 v[34:37], v[192:195], v[240:243], v[34:37]
	s_setprio 0
	s_setprio 1
	v_mfma_f32_16x16x32_bf16 v[30:33], v[196:199], v[212:215], v[30:33]
	s_add_i32 s80, 0, 0x18000
	v_mfma_f32_16x16x32_bf16 v[26:29], v[204:207], v[212:215], v[26:29]
	s_add_i32 s81, 0, 0x1c000
	v_mfma_f32_16x16x32_bf16 v[22:25], v[196:199], v[220:223], v[22:25]
	v_mfma_f32_16x16x32_bf16 v[18:21], v[204:207], v[220:223], v[18:21]
	v_mfma_f32_16x16x32_bf16 v[14:17], v[196:199], v[228:231], v[14:17]
	v_mfma_f32_16x16x32_bf16 v[10:13], v[204:207], v[228:231], v[10:13]
	v_mfma_f32_16x16x32_bf16 v[6:9], v[196:199], v[236:239], v[6:9]
	v_mfma_f32_16x16x32_bf16 v[2:5], v[204:207], v[236:239], v[2:5]
	v_mfma_f32_16x16x32_bf16 v[30:33], v[200:203], v[216:219], v[30:33]
	v_mfma_f32_16x16x32_bf16 v[26:29], v[208:211], v[216:219], v[26:29]
	v_mfma_f32_16x16x32_bf16 v[22:25], v[200:203], v[224:227], v[22:25]
	v_mfma_f32_16x16x32_bf16 v[18:21], v[208:211], v[224:227], v[18:21]
	v_mfma_f32_16x16x32_bf16 v[14:17], v[200:203], v[232:235], v[14:17]
	v_mfma_f32_16x16x32_bf16 v[10:13], v[208:211], v[232:235], v[10:13]
	v_mfma_f32_16x16x32_bf16 v[6:9], v[200:203], v[240:243], v[6:9]
	v_mfma_f32_16x16x32_bf16 v[2:5], v[208:211], v[240:243], v[2:5]
	s_setprio 0
	s_barrier
	v_add_u32_e32 v192, s80, v179
	v_add_u32_e32 v208, s81, v179
	ds_read_b128 v[132:135], v192
	ds_read_b128 v[184:187], v192 offset:1024
	ds_read_b128 v[188:191], v192 offset:2048
	ds_read_b128 v[192:195], v192 offset:3072
	ds_read_b128 v[196:199], v208
	ds_read_b128 v[200:203], v208 offset:1024
	ds_read_b128 v[204:207], v208 offset:2048
	ds_read_b128 v[208:211], v208 offset:3072
	s_mov_b32 m0, s67
	v_lshl_add_u64 v[248:249], v[246:247], 0, s[46:47]
	ds_read_b128 v[212:215], v182 offset:32768
	ds_read_b128 v[216:219], v182 offset:33792
	ds_read_b128 v[220:223], v182 offset:34816
	ds_read_b128 v[224:227], v182 offset:35840
	ds_read_b128 v[228:231], v182 offset:36864
	ds_read_b128 v[232:235], v182 offset:37888
	ds_read_b128 v[236:239], v182 offset:38912
	ds_read_b128 v[240:243], v182 offset:39936
	global_load_lds_dwordx4 v[248:249], off
	v_lshl_add_u64 v[248:249], v[246:247], 0, s[48:49]
	s_mov_b32 m0, s68
	s_nop 0
	global_load_lds_dwordx4 v[248:249], off
	s_waitcnt vmcnt(8)
	s_waitcnt lgkmcnt(0)
	s_barrier
	s_setprio 1
	s_waitcnt lgkmcnt(0)
	v_mfma_f32_16x16x32_bf16 v[126:129], v[132:135], v[212:215], v[126:129]
	v_mfma_f32_16x16x32_bf16 v[122:125], v[188:191], v[212:215], v[122:125]
	v_mfma_f32_16x16x32_bf16 v[118:121], v[132:135], v[220:223], v[118:121]
	v_mfma_f32_16x16x32_bf16 v[114:117], v[188:191], v[220:223], v[114:117]
	v_mfma_f32_16x16x32_bf16 v[110:113], v[132:135], v[228:231], v[110:113]
	v_mfma_f32_16x16x32_bf16 v[106:109], v[188:191], v[228:231], v[106:109]
	v_mfma_f32_16x16x32_bf16 v[102:105], v[132:135], v[236:239], v[102:105]
	v_mfma_f32_16x16x32_bf16 v[98:101], v[188:191], v[236:239], v[98:101]
	v_mfma_f32_16x16x32_bf16 v[126:129], v[184:187], v[216:219], v[126:129]
	v_mfma_f32_16x16x32_bf16 v[122:125], v[192:195], v[216:219], v[122:125]
	v_mfma_f32_16x16x32_bf16 v[118:121], v[184:187], v[224:227], v[118:121]
	v_mfma_f32_16x16x32_bf16 v[114:117], v[192:195], v[224:227], v[114:117]
	v_mfma_f32_16x16x32_bf16 v[110:113], v[184:187], v[232:235], v[110:113]
	v_mfma_f32_16x16x32_bf16 v[106:109], v[192:195], v[232:235], v[106:109]
	v_mfma_f32_16x16x32_bf16 v[102:105], v[184:187], v[240:243], v[102:105]
	v_mfma_f32_16x16x32_bf16 v[98:101], v[192:195], v[240:243], v[98:101]
	s_setprio 0
	s_setprio 1
	v_mfma_f32_16x16x32_bf16 v[94:97], v[196:199], v[212:215], v[94:97]
	s_add_i32 s80, s80, s21
	v_mfma_f32_16x16x32_bf16 v[90:93], v[204:207], v[212:215], v[90:93]
	s_mov_b32 m0, s80
	v_mfma_f32_16x16x32_bf16 v[86:89], v[196:199], v[220:223], v[86:89]
	v_mfma_f32_16x16x32_bf16 v[82:85], v[204:207], v[220:223], v[82:85]
	v_mfma_f32_16x16x32_bf16 v[78:81], v[196:199], v[228:231], v[78:81]
	v_mfma_f32_16x16x32_bf16 v[74:77], v[204:207], v[228:231], v[74:77]
	v_mfma_f32_16x16x32_bf16 v[70:73], v[196:199], v[236:239], v[70:73]
	v_mfma_f32_16x16x32_bf16 v[66:69], v[204:207], v[236:239], v[66:69]
	v_mfma_f32_16x16x32_bf16 v[94:97], v[200:203], v[216:219], v[94:97]
	v_mfma_f32_16x16x32_bf16 v[90:93], v[208:211], v[216:219], v[90:93]
	v_mfma_f32_16x16x32_bf16 v[86:89], v[200:203], v[224:227], v[86:89]
	v_lshl_add_u64 v[136:137], v[136:137], 0, s[30:31]
	v_mfma_f32_16x16x32_bf16 v[82:85], v[208:211], v[224:227], v[82:85]
	v_mfma_f32_16x16x32_bf16 v[78:81], v[200:203], v[232:235], v[78:81]
	v_mfma_f32_16x16x32_bf16 v[74:77], v[208:211], v[232:235], v[74:77]
	v_mfma_f32_16x16x32_bf16 v[70:73], v[200:203], v[240:243], v[70:73]
	v_mfma_f32_16x16x32_bf16 v[66:69], v[208:211], v[240:243], v[66:69]
	s_setprio 0
	s_barrier
; #define PG8_STAGE(bufoff, gbase, voff) do { _Pragma("unroll") for (int _i = 0; _i < 2; ++_i) \
;         __builtin_amdgcn_global_load_lds((const unsigned*)((const char*)(gbase) + (voff)[_i]), (PG8_LAS unsigned*)(lds + (bufoff) + ldsw + _i * 8192), 16, 0, 0); } while (0)
; #define PG8_LDA(dst, b, h) do { _Pragma("unroll") for (int m = 0; m < 4; ++m) _Pragma("unroll") for (int k = 0; k < 2; ++k) dst[m][k] = *(const PG8_LAS bf16x8*)(lds + PG8_SA(b, h) + aoff + m * 2048 + k * 1024); } while (0)
; #define PG8_MMA(ai, bj, At, Bt) do { __builtin_amdgcn_s_setprio(1); _Pragma("unroll") for (int m = 0; m < 4; ++m) _Pragma("unroll") for (int n = 0; n < 2; ++n) _Pragma("unroll") for (int k = 0; k < 2; ++k) \
;         acc[ai][bj][m][n] = __builtin_amdgcn_mfma_f32_16x16x32_bf16(Bt[n][k], At[m][k], acc[ai][bj][m][n], 0, 0, 0); __builtin_amdgcn_s_setprio(0); } while (0)
; #define PG8_WAIT_V(n) asm volatile("s_waitcnt vmcnt(" #n ")" ::: "memory")
; #define PG8_WAIT_L(n) asm volatile("s_waitcnt lgkmcnt(" #n ")" ::: "memory")
; #define PG8_BAR __builtin_amdgcn_s_barrier()
; #define PG8_SCHED __builtin_amdgcn_sched_barrier(0)
; template <class Epi, bool ALIGN_EPI, bool ABLK = false>
; __device__ __forceinline__ void gemm_phase(PG8_LAS unsigned char* lds, const Gemm g, const StaticOrder& S, const Epi& E) {
;     ...
;             PG8_LDA(At, 1, 1); PG8_STAGE(PG8_SB(1, 0), b3, voffB); PG8_STAGE(PG8_SB(1, 1), b3 + hstepB, voffB); PG8_STAGE(PG8_SA(1, 0), a3, voffA);
;             PG8_WAIT_V(8); PG8_WAIT_L(0); PG8_BAR; PG8_MMA(1, 0, At, B0); PG8_MMA(1, 1, At, B1); PG8_BAR; PG8_SCHED;
;         }
	ds_read_b128 v[212:215], v182 offset:49152
	ds_read_b128 v[216:219], v182 offset:50176
	ds_read_b128 v[220:223], v182 offset:51200
	ds_read_b128 v[224:227], v182 offset:52224
	ds_read_b128 v[228:231], v182 offset:53248
	ds_read_b128 v[232:235], v182 offset:54272
	ds_read_b128 v[236:239], v182 offset:55296
	ds_read_b128 v[240:243], v182 offset:56320
	global_load_lds_dwordx4 v[136:137], off
	s_add_i32 m0, s80, 0x2000
	s_add_u32 s62, s62, 0x40080
	v_lshl_add_u64 v[136:137], v[244:245], 0, s[30:31]
	s_addc_u32 s63, s63, 0
	s_add_i32 s80, s81, s21
	global_load_lds_dwordx4 v[136:137], off
	v_lshl_add_u64 v[136:137], s[62:63], 0, v[140:141]
	s_mov_b32 m0, s80
	s_nop 0
	global_load_lds_dwordx4 v[136:137], off
	v_lshl_add_u64 v[136:137], s[62:63], 0, v[142:143]
	s_add_i32 m0, s80, 0x2000
	s_nop 0
	global_load_lds_dwordx4 v[136:137], off
	v_lshl_add_u64 v[136:137], v[246:247], 0, s[34:35]
	s_mov_b32 m0, s9
	s_nop 0
	global_load_lds_dwordx4 v[136:137], off
	v_lshl_add_u64 v[136:137], v[246:247], 0, s[36:37]
	s_mov_b32 m0, s70
	s_nop 0
	global_load_lds_dwordx4 v[136:137], off
	s_waitcnt vmcnt(8)
	s_waitcnt lgkmcnt(0)
	s_barrier
	s_setprio 1
	s_waitcnt lgkmcnt(0)
	v_mfma_f32_16x16x32_bf16 v[62:65], v[132:135], v[212:215], v[62:65]
	v_mfma_f32_16x16x32_bf16 v[58:61], v[188:191], v[212:215], v[58:61]
	v_mfma_f32_16x16x32_bf16 v[54:57], v[132:135], v[220:223], v[54:57]
	v_mfma_f32_16x16x32_bf16 v[50:53], v[188:191], v[220:223], v[50:53]
	v_mfma_f32_16x16x32_bf16 v[46:49], v[132:135], v[228:231], v[46:49]
	v_mfma_f32_16x16x32_bf16 v[42:45], v[188:191], v[228:231], v[42:45]
	v_mfma_f32_16x16x32_bf16 v[38:41], v[132:135], v[236:239], v[38:41]
	v_mfma_f32_16x16x32_bf16 v[34:37], v[188:191], v[236:239], v[34:37]
	v_mfma_f32_16x16x32_bf16 v[62:65], v[184:187], v[216:219], v[62:65]
	v_mfma_f32_16x16x32_bf16 v[58:61], v[192:195], v[216:219], v[58:61]
	v_mfma_f32_16x16x32_bf16 v[54:57], v[184:187], v[224:227], v[54:57]
	v_mfma_f32_16x16x32_bf16 v[50:53], v[192:195], v[224:227], v[50:53]
	v_mfma_f32_16x16x32_bf16 v[46:49], v[184:187], v[232:235], v[46:49]
	v_mfma_f32_16x16x32_bf16 v[42:45], v[192:195], v[232:235], v[42:45]
	v_mfma_f32_16x16x32_bf16 v[38:41], v[184:187], v[240:243], v[38:41]
	v_mfma_f32_16x16x32_bf16 v[34:37], v[192:195], v[240:243], v[34:37]
	s_setprio 0
	s_setprio 1
	v_mfma_f32_16x16x32_bf16 v[30:33], v[196:199], v[212:215], v[30:33]
	s_add_i32 s79, s79, 2
	v_mfma_f32_16x16x32_bf16 v[26:29], v[204:207], v[212:215], v[26:29]
	s_add_u32 s77, s77, 0x100
	v_mfma_f32_16x16x32_bf16 v[22:25], v[196:199], v[220:223], v[22:25]
	s_addc_u32 s78, s78, 0
	v_mfma_f32_16x16x32_bf16 v[18:21], v[204:207], v[220:223], v[18:21]
	s_add_u32 s60, s60, 0x10000
	v_mfma_f32_16x16x32_bf16 v[14:17], v[196:199], v[228:231], v[14:17]
	s_addc_u32 s61, s61, 0
	v_mfma_f32_16x16x32_bf16 v[10:13], v[204:207], v[228:231], v[10:13]
	s_cmp_gt_u32 s79, 13
	v_mfma_f32_16x16x32_bf16 v[6:9], v[196:199], v[236:239], v[6:9]
	v_mfma_f32_16x16x32_bf16 v[2:5], v[204:207], v[236:239], v[2:5]
	v_mfma_f32_16x16x32_bf16 v[30:33], v[200:203], v[216:219], v[30:33]
	v_mfma_f32_16x16x32_bf16 v[26:29], v[208:211], v[216:219], v[26:29]
	v_mfma_f32_16x16x32_bf16 v[22:25], v[200:203], v[224:227], v[22:25]
	v_lshl_add_u64 v[130:131], v[130:131], 0, s[50:51]
	v_mfma_f32_16x16x32_bf16 v[18:21], v[208:211], v[224:227], v[18:21]
	v_mfma_f32_16x16x32_bf16 v[14:17], v[200:203], v[232:235], v[14:17]
	v_mfma_f32_16x16x32_bf16 v[10:13], v[208:211], v[232:235], v[10:13]
	v_mfma_f32_16x16x32_bf16 v[6:9], v[200:203], v[240:243], v[6:9]
	v_mfma_f32_16x16x32_bf16 v[2:5], v[208:211], v[240:243], v[2:5]
	s_setprio 0
	s_barrier
	s_cbranch_scc0 .LBB0_1983
	s_and_b64 vcc, exec, s[38:39]
	s_cbranch_vccz .LBB0_1986
	s_barrier

; #define PG8_STAGE(bufoff, gbase, voff) do { _Pragma("unroll") for (int _i = 0; _i < 2; ++_i) \
;         __builtin_amdgcn_global_load_lds((const unsigned*)((const char*)(gbase) + (voff)[_i]), (PG8_LAS unsigned*)(lds + (bufoff) + ldsw + _i * 8192), 16, 0, 0); } while (0)
; #define PG8_LDA(dst, b, h) do { _Pragma("unroll") for (int m = 0; m < 4; ++m) _Pragma("unroll") for (int k = 0; k < 2; ++k) dst[m][k] = *(const PG8_LAS bf16x8*)(lds + PG8_SA(b, h) + aoff + m * 2048 + k * 1024); } while (0)
; #define PG8_LDB(dst, b, h) do { _Pragma("unroll") for (int n = 0; n < 2; ++n) _Pragma("unroll") for (int k = 0; k < 2; ++k) dst[n][k] = *(const PG8_LAS bf16x8*)(lds + PG8_SB(b, h) + boff + n * 2048 + k * 1024); } while (0)
; #define PG8_MMA(ai, bj, At, Bt) do { __builtin_amdgcn_s_setprio(1); _Pragma("unroll") for (int m = 0; m < 4; ++m) _Pragma("unroll") for (int n = 0; n < 2; ++n) _Pragma("unroll") for (int k = 0; k < 2; ++k) \
;         acc[ai][bj][m][n] = __builtin_amdgcn_mfma_f32_16x16x32_bf16(Bt[n][k], At[m][k], acc[ai][bj][m][n], 0, 0, 0); __builtin_amdgcn_s_setprio(0); } while (0)
; #define PG8_WAIT_V(n) asm volatile("s_waitcnt vmcnt(" #n ")" ::: "memory")
; #define PG8_WAIT_L(n) asm volatile("s_waitcnt lgkmcnt(" #n ")" ::: "memory")
; #define PG8_BAR __builtin_amdgcn_s_barrier()
; #define PG8_SCHED __builtin_amdgcn_sched_barrier(0)
; template <class Epi, bool ALIGN_EPI, bool ABLK = false>
; __device__ __forceinline__ void gemm_phase(PG8_LAS unsigned char* lds, const Gemm g, const StaticOrder& S, const Epi& E) {
;     ...
;             const char* a1 = cA + (size_t)(t + 1) * kstepA;
;             const char* a2 = last ? nA : cA + (size_t)(t + 2) * kstepA; const char* b2 = last ? nB : cB + (size_t)(t + 2) * kstepB;
;             const char* a3 = a2 + kstepA; const char* b3 = b2 + kstepB;
;             PG8_LDB(B0, 0, 0); PG8_LDB(B1, 0, 1); PG8_SCHED; PG8_LDA(At, 0, 0); PG8_STAGE(PG8_SA(1, 1), a1 + hstepA, voffA);
;             PG8_WAIT_V(8); PG8_WAIT_L(0); PG8_BAR; PG8_MMA(0, 0, At, B0); PG8_MMA(0, 1, At, B1); PG8_BAR; PG8_SCHED;
;             PG8_LDA(At, 0, 1); PG8_STAGE(PG8_SB(0, 0), b2, voffB); PG8_STAGE(PG8_SB(0, 1), b2 + hstepB, voffB); PG8_STAGE(PG8_SA(0, 0), a2, voffA);
.LBB0_2105:
	v_add_u32_e32 v3, s64, v239
	ds_read_b128 v[134:137], v3
	ds_read_b128 v[138:141], v3 offset:1024
	ds_read_b128 v[142:145], v3 offset:2048
	ds_read_b128 v[146:149], v3 offset:3072
	v_add_u32_e32 v3, s65, v239
	ds_read_b128 v[150:153], v3
	ds_read_b128 v[154:157], v3 offset:1024
	ds_read_b128 v[158:161], v3 offset:2048
	ds_read_b128 v[162:165], v3 offset:3072
	s_add_u32 s48, s6, 0xfffc0080
	s_addc_u32 s49, s7, -1
	s_cmp_eq_u32 s73, 12
	s_cselect_b32 s51, s43, s49
	s_cselect_b32 s50, s69, s48
	s_cselect_b32 s49, s41, s72
	s_cselect_b32 s48, s70, s71
	v_lshl_add_u64 v[4:5], s[6:7], 0, v[218:219]
	s_add_i32 m0, s37, 0xc000
	ds_read_b128 v[166:169], v240
	ds_read_b128 v[170:173], v240 offset:1024
	ds_read_b128 v[174:177], v240 offset:2048
	ds_read_b128 v[178:181], v240 offset:3072
	ds_read_b128 v[182:185], v240 offset:4096
	ds_read_b128 v[186:189], v240 offset:5120
	ds_read_b128 v[190:193], v240 offset:6144
	ds_read_b128 v[226:229], v240 offset:7168
	global_load_lds_dwordx4 v[4:5], off
	v_lshl_add_u64 v[4:5], s[6:7], 0, v[220:221]
	s_add_i32 m0, s37, 0xe000
	s_nop 0
	global_load_lds_dwordx4 v[4:5], off
	s_waitcnt vmcnt(8)
	s_waitcnt lgkmcnt(0)
	s_barrier
	s_setprio 1
	s_waitcnt lgkmcnt(0)
	v_mfma_f32_16x16x32_bf16 v[130:133], v[134:137], v[166:169], v[130:133]
	v_mfma_f32_16x16x32_bf16 v[126:129], v[142:145], v[166:169], v[126:129]
	v_mfma_f32_16x16x32_bf16 v[122:125], v[134:137], v[174:177], v[122:125]
	v_mfma_f32_16x16x32_bf16 v[118:121], v[142:145], v[174:177], v[118:121]
	v_mfma_f32_16x16x32_bf16 v[114:117], v[134:137], v[182:185], v[114:117]
	v_mfma_f32_16x16x32_bf16 v[110:113], v[142:145], v[182:185], v[110:113]
	v_mfma_f32_16x16x32_bf16 v[106:109], v[134:137], v[190:193], v[106:109]
	v_mfma_f32_16x16x32_bf16 v[102:105], v[142:145], v[190:193], v[102:105]
	v_mfma_f32_16x16x32_bf16 v[130:133], v[138:141], v[170:173], v[130:133]
	v_mfma_f32_16x16x32_bf16 v[126:129], v[146:149], v[170:173], v[126:129]
	v_mfma_f32_16x16x32_bf16 v[122:125], v[138:141], v[178:181], v[122:125]
	v_mfma_f32_16x16x32_bf16 v[118:121], v[146:149], v[178:181], v[118:121]
	v_mfma_f32_16x16x32_bf16 v[114:117], v[138:141], v[186:189], v[114:117]
	v_mfma_f32_16x16x32_bf16 v[110:113], v[146:149], v[186:189], v[110:113]
	v_mfma_f32_16x16x32_bf16 v[106:109], v[138:141], v[226:229], v[106:109]
	v_mfma_f32_16x16x32_bf16 v[102:105], v[146:149], v[226:229], v[102:105]
	s_setprio 0
	s_setprio 1
	v_mfma_f32_16x16x32_bf16 v[98:101], v[150:153], v[166:169], v[98:101]
	s_add_i32 s74, s64, s54
	v_mfma_f32_16x16x32_bf16 v[94:97], v[158:161], v[166:169], v[94:97]
	s_mov_b32 m0, s74
	v_mfma_f32_16x16x32_bf16 v[90:93], v[150:153], v[174:177], v[90:93]
	v_mfma_f32_16x16x32_bf16 v[86:89], v[158:161], v[174:177], v[86:89]
	v_mfma_f32_16x16x32_bf16 v[82:85], v[150:153], v[182:185], v[82:85]
	v_mfma_f32_16x16x32_bf16 v[78:81], v[158:161], v[182:185], v[78:81]
	v_mfma_f32_16x16x32_bf16 v[74:77], v[150:153], v[190:193], v[74:77]
	v_mfma_f32_16x16x32_bf16 v[70:73], v[158:161], v[190:193], v[70:73]
	v_mfma_f32_16x16x32_bf16 v[98:101], v[154:157], v[170:173], v[98:101]
	v_mfma_f32_16x16x32_bf16 v[94:97], v[162:165], v[170:173], v[94:97]
	v_mfma_f32_16x16x32_bf16 v[90:93], v[154:157], v[178:181], v[90:93]
	v_lshl_add_u64 v[230:231], s[48:49], 0, v[196:197]
	v_mfma_f32_16x16x32_bf16 v[86:89], v[162:165], v[178:181], v[86:89]
	v_mfma_f32_16x16x32_bf16 v[82:85], v[154:157], v[186:189], v[82:85]
	v_mfma_f32_16x16x32_bf16 v[78:81], v[162:165], v[186:189], v[78:81]
	v_mfma_f32_16x16x32_bf16 v[74:77], v[154:157], v[226:229], v[74:77]
	v_mfma_f32_16x16x32_bf16 v[70:73], v[162:165], v[226:229], v[70:73]
	s_setprio 0
	s_barrier
	ds_read_b128 v[166:169], v240 offset:16384
	ds_read_b128 v[170:173], v240 offset:17408
	ds_read_b128 v[174:177], v240 offset:18432
	ds_read_b128 v[178:181], v240 offset:19456
	ds_read_b128 v[182:185], v240 offset:20480
	ds_read_b128 v[186:189], v240 offset:21504
	ds_read_b128 v[190:193], v240 offset:22528
	ds_read_b128 v[226:229], v240 offset:23552
	global_load_lds_dwordx4 v[230:231], off
	s_add_i32 m0, s74, 0x2000
	s_add_u32 s74, s48, 0x80000
	v_lshl_add_u64 v[242:243], s[48:49], 0, v[200:201]
	s_addc_u32 s75, s49, 0
	s_add_i32 s76, s65, s54
	global_load_lds_dwordx4 v[242:243], off
	v_lshl_add_u64 v[4:5], s[74:75], 0, v[196:197]
	s_mov_b32 m0, s76
	v_lshl_add_u64 v[244:245], s[50:51], 0, v[194:195]
	global_load_lds_dwordx4 v[4:5], off
	v_lshl_add_u64 v[4:5], s[74:75], 0, v[200:201]
	s_add_i32 m0, s76, 0x2000
	v_lshl_add_u64 v[246:247], s[50:51], 0, v[198:199]
	global_load_lds_dwordx4 v[4:5], off
	s_mov_b32 m0, s37
	s_nop 0
	global_load_lds_dwordx4 v[244:245], off
	s_mov_b32 m0, s39
	s_nop 0
	global_load_lds_dwordx4 v[246:247], off
	s_waitcnt vmcnt(8)
	s_waitcnt lgkmcnt(0)
	s_barrier
; #define PG8_STAGE(bufoff, gbase, voff) do { _Pragma("unroll") for (int _i = 0; _i < 2; ++_i) \
;         __builtin_amdgcn_global_load_lds((const unsigned*)((const char*)(gbase) + (voff)[_i]), (PG8_LAS unsigned*)(lds + (bufoff) + ldsw + _i * 8192), 16, 0, 0); } while (0)
; #define PG8_LDA(dst, b, h) do { _Pragma("unroll") for (int m = 0; m < 4; ++m) _Pragma("unroll") for (int k = 0; k < 2; ++k) dst[m][k] = *(const PG8_LAS bf16x8*)(lds + PG8_SA(b, h) + aoff + m * 2048 + k * 1024); } while (0)
; #define PG8_LDB(dst, b, h) do { _Pragma("unroll") for (int n = 0; n < 2; ++n) _Pragma("unroll") for (int k = 0; k < 2; ++k) dst[n][k] = *(const PG8_LAS bf16x8*)(lds + PG8_SB(b, h) + boff + n * 2048 + k * 1024); } while (0)
; #define PG8_MMA(ai, bj, At, Bt) do { __builtin_amdgcn_s_setprio(1); _Pragma("unroll") for (int m = 0; m < 4; ++m) _Pragma("unroll") for (int n = 0; n < 2; ++n) _Pragma("unroll") for (int k = 0; k < 2; ++k) \
;         acc[ai][bj][m][n] = __builtin_amdgcn_mfma_f32_16x16x32_bf16(Bt[n][k], At[m][k], acc[ai][bj][m][n], 0, 0, 0); __builtin_amdgcn_s_setprio(0); } while (0)
; #define PG8_WAIT_V(n) asm volatile("s_waitcnt vmcnt(" #n ")" ::: "memory")
; #define PG8_WAIT_L(n) asm volatile("s_waitcnt lgkmcnt(" #n ")" ::: "memory")
; #define PG8_BAR __builtin_amdgcn_s_barrier()
; #define PG8_SCHED __builtin_amdgcn_sched_barrier(0)
; template <class Epi, bool ALIGN_EPI, bool ABLK = false>
; __device__ __forceinline__ void gemm_phase(PG8_LAS unsigned char* lds, const Gemm g, const StaticOrder& S, const Epi& E) {
;     ...
;             PG8_WAIT_V(8); PG8_WAIT_L(0); PG8_BAR; PG8_MMA(1, 0, At, B0); PG8_MMA(1, 1, At, B1); PG8_BAR; PG8_SCHED;
;             PG8_LDB(B0, 1, 0); PG8_LDB(B1, 1, 1); PG8_SCHED; PG8_LDA(At, 1, 0); PG8_STAGE(PG8_SA(0, 1), a2 + hstepA, voffA);
;             PG8_WAIT_V(8); PG8_WAIT_L(0); PG8_BAR; PG8_MMA(0, 0, At, B0); PG8_MMA(0, 1, At, B1); PG8_BAR; PG8_SCHED;
	s_setprio 1
	s_waitcnt lgkmcnt(0)
	v_mfma_f32_16x16x32_bf16 v[66:69], v[134:137], v[166:169], v[66:69]
	v_mfma_f32_16x16x32_bf16 v[62:65], v[142:145], v[166:169], v[62:65]
	v_mfma_f32_16x16x32_bf16 v[58:61], v[134:137], v[174:177], v[58:61]
	v_mfma_f32_16x16x32_bf16 v[54:57], v[142:145], v[174:177], v[54:57]
	v_mfma_f32_16x16x32_bf16 v[50:53], v[134:137], v[182:185], v[50:53]
	v_mfma_f32_16x16x32_bf16 v[46:49], v[142:145], v[182:185], v[46:49]
	v_mfma_f32_16x16x32_bf16 v[42:45], v[134:137], v[190:193], v[42:45]
	v_mfma_f32_16x16x32_bf16 v[38:41], v[142:145], v[190:193], v[38:41]
	v_mfma_f32_16x16x32_bf16 v[66:69], v[138:141], v[170:173], v[66:69]
	v_mfma_f32_16x16x32_bf16 v[62:65], v[146:149], v[170:173], v[62:65]
	v_mfma_f32_16x16x32_bf16 v[58:61], v[138:141], v[178:181], v[58:61]
	v_mfma_f32_16x16x32_bf16 v[54:57], v[146:149], v[178:181], v[54:57]
	v_mfma_f32_16x16x32_bf16 v[50:53], v[138:141], v[186:189], v[50:53]
	v_mfma_f32_16x16x32_bf16 v[46:49], v[146:149], v[186:189], v[46:49]
	v_mfma_f32_16x16x32_bf16 v[42:45], v[138:141], v[226:229], v[42:45]
	v_mfma_f32_16x16x32_bf16 v[38:41], v[146:149], v[226:229], v[38:41]
	s_setprio 0
	s_setprio 1
	v_mfma_f32_16x16x32_bf16 v[34:37], v[150:153], v[166:169], v[34:37]
	s_add_i32 s74, 0, 0x18000
	v_mfma_f32_16x16x32_bf16 v[30:33], v[158:161], v[166:169], v[30:33]
	s_add_i32 s75, 0, 0x1c000
	v_mfma_f32_16x16x32_bf16 v[26:29], v[150:153], v[174:177], v[26:29]
	v_mfma_f32_16x16x32_bf16 v[22:25], v[158:161], v[174:177], v[22:25]
	v_mfma_f32_16x16x32_bf16 v[18:21], v[150:153], v[182:185], v[18:21]
	v_mfma_f32_16x16x32_bf16 v[14:17], v[158:161], v[182:185], v[14:17]
	v_mfma_f32_16x16x32_bf16 v[10:13], v[150:153], v[190:193], v[10:13]
	v_mfma_f32_16x16x32_bf16 v[4:7], v[158:161], v[190:193], v[6:9]
	v_mfma_f32_16x16x32_bf16 v[34:37], v[154:157], v[170:173], v[34:37]
	v_mfma_f32_16x16x32_bf16 v[30:33], v[162:165], v[170:173], v[30:33]
	v_mfma_f32_16x16x32_bf16 v[26:29], v[154:157], v[178:181], v[26:29]
	v_add_u32_e32 v3, s74, v239
	v_mfma_f32_16x16x32_bf16 v[22:25], v[162:165], v[178:181], v[22:25]
	v_mfma_f32_16x16x32_bf16 v[18:21], v[154:157], v[186:189], v[18:21]
	v_mfma_f32_16x16x32_bf16 v[14:17], v[162:165], v[186:189], v[14:17]
	v_mfma_f32_16x16x32_bf16 v[10:13], v[154:157], v[226:229], v[10:13]
	v_mfma_f32_16x16x32_bf16 v[4:7], v[162:165], v[226:229], v[4:7]
	s_setprio 0
	s_barrier
	ds_read_b128 v[134:137], v3
	ds_read_b128 v[138:141], v3 offset:1024
	ds_read_b128 v[142:145], v3 offset:2048
	ds_read_b128 v[146:149], v3 offset:3072
	v_add_u32_e32 v3, s75, v239
	ds_read_b128 v[150:153], v3
	ds_read_b128 v[154:157], v3 offset:1024
	ds_read_b128 v[158:161], v3 offset:2048
	ds_read_b128 v[162:165], v3 offset:3072
	s_add_u32 s50, s50, 0x40000
	s_addc_u32 s51, s51, 0
	s_mov_b32 m0, s55
	v_lshl_add_u64 v[8:9], s[50:51], 0, v[194:195]
	ds_read_b128 v[166:169], v240 offset:32768
	ds_read_b128 v[170:173], v240 offset:33792
	ds_read_b128 v[174:177], v240 offset:34816
	ds_read_b128 v[178:181], v240 offset:35840
	ds_read_b128 v[182:185], v240 offset:36864
	ds_read_b128 v[186:189], v240 offset:37888
	ds_read_b128 v[190:193], v240 offset:38912
	ds_read_b128 v[226:229], v240 offset:39936
	global_load_lds_dwordx4 v[8:9], off
	v_lshl_add_u64 v[8:9], s[50:51], 0, v[198:199]
	s_mov_b32 m0, s56
	s_nop 0
	global_load_lds_dwordx4 v[8:9], off
	s_waitcnt vmcnt(8)
	s_waitcnt lgkmcnt(0)
	s_barrier
	s_setprio 1
	s_waitcnt lgkmcnt(0)
	v_mfma_f32_16x16x32_bf16 v[130:133], v[134:137], v[166:169], v[130:133]
	v_mfma_f32_16x16x32_bf16 v[126:129], v[142:145], v[166:169], v[126:129]
	v_mfma_f32_16x16x32_bf16 v[122:125], v[134:137], v[174:177], v[122:125]
	v_mfma_f32_16x16x32_bf16 v[118:121], v[142:145], v[174:177], v[118:121]
	v_mfma_f32_16x16x32_bf16 v[114:117], v[134:137], v[182:185], v[114:117]
	v_mfma_f32_16x16x32_bf16 v[110:113], v[142:145], v[182:185], v[110:113]
	v_mfma_f32_16x16x32_bf16 v[106:109], v[134:137], v[190:193], v[106:109]
	v_mfma_f32_16x16x32_bf16 v[102:105], v[142:145], v[190:193], v[102:105]
	v_mfma_f32_16x16x32_bf16 v[130:133], v[138:141], v[170:173], v[130:133]
	v_mfma_f32_16x16x32_bf16 v[126:129], v[146:149], v[170:173], v[126:129]
	v_mfma_f32_16x16x32_bf16 v[122:125], v[138:141], v[178:181], v[122:125]
	v_mfma_f32_16x16x32_bf16 v[118:121], v[146:149], v[178:181], v[118:121]
	v_mfma_f32_16x16x32_bf16 v[114:117], v[138:141], v[186:189], v[114:117]
	v_mfma_f32_16x16x32_bf16 v[110:113], v[146:149], v[186:189], v[110:113]
	v_mfma_f32_16x16x32_bf16 v[106:109], v[138:141], v[226:229], v[106:109]
	v_mfma_f32_16x16x32_bf16 v[102:105], v[146:149], v[226:229], v[102:105]
	s_setprio 0
	s_setprio 1
	v_mfma_f32_16x16x32_bf16 v[98:101], v[150:153], v[166:169], v[98:101]
	s_add_i32 s50, s74, s54
	v_mfma_f32_16x16x32_bf16 v[94:97], v[158:161], v[166:169], v[94:97]
	s_mov_b32 m0, s50
	v_mfma_f32_16x16x32_bf16 v[90:93], v[150:153], v[174:177], v[90:93]
	v_mfma_f32_16x16x32_bf16 v[86:89], v[158:161], v[174:177], v[86:89]
	v_mfma_f32_16x16x32_bf16 v[82:85], v[150:153], v[182:185], v[82:85]
	v_mfma_f32_16x16x32_bf16 v[78:81], v[158:161], v[182:185], v[78:81]
	v_mfma_f32_16x16x32_bf16 v[74:77], v[150:153], v[190:193], v[74:77]
	v_mfma_f32_16x16x32_bf16 v[70:73], v[158:161], v[190:193], v[70:73]
	v_mfma_f32_16x16x32_bf16 v[98:101], v[154:157], v[170:173], v[98:101]
	v_mfma_f32_16x16x32_bf16 v[94:97], v[162:165], v[170:173], v[94:97]
	v_mfma_f32_16x16x32_bf16 v[90:93], v[154:157], v[178:181], v[90:93]
	v_lshl_add_u64 v[8:9], v[230:231], 0, s[22:23]
	v_mfma_f32_16x16x32_bf16 v[86:89], v[162:165], v[178:181], v[86:89]
	v_mfma_f32_16x16x32_bf16 v[82:85], v[154:157], v[186:189], v[82:85]
	v_mfma_f32_16x16x32_bf16 v[78:81], v[162:165], v[186:189], v[78:81]
	v_mfma_f32_16x16x32_bf16 v[74:77], v[154:157], v[226:229], v[74:77]
	v_mfma_f32_16x16x32_bf16 v[70:73], v[162:165], v[226:229], v[70:73]
	s_setprio 0
	s_barrier
; #define PG8_STAGE(bufoff, gbase, voff) do { _Pragma("unroll") for (int _i = 0; _i < 2; ++_i) \
;         __builtin_amdgcn_global_load_lds((const unsigned*)((const char*)(gbase) + (voff)[_i]), (PG8_LAS unsigned*)(lds + (bufoff) + ldsw + _i * 8192), 16, 0, 0); } while (0)
; #define PG8_LDA(dst, b, h) do { _Pragma("unroll") for (int m = 0; m < 4; ++m) _Pragma("unroll") for (int k = 0; k < 2; ++k) dst[m][k] = *(const PG8_LAS bf16x8*)(lds + PG8_SA(b, h) + aoff + m * 2048 + k * 1024); } while (0)
; #define PG8_MMA(ai, bj, At, Bt) do { __builtin_amdgcn_s_setprio(1); _Pragma("unroll") for (int m = 0; m < 4; ++m) _Pragma("unroll") for (int n = 0; n < 2; ++n) _Pragma("unroll") for (int k = 0; k < 2; ++k) \
;         acc[ai][bj][m][n] = __builtin_amdgcn_mfma_f32_16x16x32_bf16(Bt[n][k], At[m][k], acc[ai][bj][m][n], 0, 0, 0); __builtin_amdgcn_s_setprio(0); } while (0)
; #define PG8_WAIT_V(n) asm volatile("s_waitcnt vmcnt(" #n ")" ::: "memory")
; #define PG8_WAIT_L(n) asm volatile("s_waitcnt lgkmcnt(" #n ")" ::: "memory")
; #define PG8_BAR __builtin_amdgcn_s_barrier()
; #define PG8_SCHED __builtin_amdgcn_sched_barrier(0)
; template <class Epi, bool ALIGN_EPI, bool ABLK = false>
; __device__ __forceinline__ void gemm_phase(PG8_LAS unsigned char* lds, const Gemm g, const StaticOrder& S, const Epi& E) {
;     ...
;             PG8_LDA(At, 1, 1); PG8_STAGE(PG8_SB(1, 0), b3, voffB); PG8_STAGE(PG8_SB(1, 1), b3 + hstepB, voffB); PG8_STAGE(PG8_SA(1, 0), a3, voffA);
;             PG8_WAIT_V(8); PG8_WAIT_L(0); PG8_BAR; PG8_MMA(1, 0, At, B0); PG8_MMA(1, 1, At, B1); PG8_BAR; PG8_SCHED;
;         }
	ds_read_b128 v[166:169], v240 offset:49152
	ds_read_b128 v[170:173], v240 offset:50176
	ds_read_b128 v[174:177], v240 offset:51200
	ds_read_b128 v[178:181], v240 offset:52224
	ds_read_b128 v[182:185], v240 offset:53248
	ds_read_b128 v[186:189], v240 offset:54272
	ds_read_b128 v[190:193], v240 offset:55296
	ds_read_b128 v[226:229], v240 offset:56320
	global_load_lds_dwordx4 v[8:9], off
	s_add_i32 m0, s50, 0x2000
	s_add_u32 s48, s48, 0x80080
	v_lshl_add_u64 v[8:9], v[242:243], 0, s[22:23]
	s_addc_u32 s49, s49, 0
	s_add_i32 s50, s75, s54
	global_load_lds_dwordx4 v[8:9], off
	v_lshl_add_u64 v[8:9], s[48:49], 0, v[196:197]
	s_mov_b32 m0, s50
	s_nop 0
	global_load_lds_dwordx4 v[8:9], off
	v_lshl_add_u64 v[8:9], s[48:49], 0, v[200:201]
	s_add_i32 m0, s50, 0x2000
	s_nop 0
	global_load_lds_dwordx4 v[8:9], off
	v_lshl_add_u64 v[8:9], v[244:245], 0, s[22:23]
	s_mov_b32 m0, s59
	s_nop 0
	global_load_lds_dwordx4 v[8:9], off
	v_lshl_add_u64 v[8:9], v[246:247], 0, s[22:23]
	s_mov_b32 m0, s60
	s_nop 0
	global_load_lds_dwordx4 v[8:9], off
	s_waitcnt vmcnt(8)
	s_waitcnt lgkmcnt(0)
	s_barrier
	s_setprio 1
	s_waitcnt lgkmcnt(0)
	v_mfma_f32_16x16x32_bf16 v[66:69], v[134:137], v[166:169], v[66:69]
	v_mfma_f32_16x16x32_bf16 v[62:65], v[142:145], v[166:169], v[62:65]
	v_mfma_f32_16x16x32_bf16 v[58:61], v[134:137], v[174:177], v[58:61]
	v_mfma_f32_16x16x32_bf16 v[54:57], v[142:145], v[174:177], v[54:57]
	v_mfma_f32_16x16x32_bf16 v[50:53], v[134:137], v[182:185], v[50:53]
	v_mfma_f32_16x16x32_bf16 v[46:49], v[142:145], v[182:185], v[46:49]
	v_mfma_f32_16x16x32_bf16 v[42:45], v[134:137], v[190:193], v[42:45]
	v_mfma_f32_16x16x32_bf16 v[38:41], v[142:145], v[190:193], v[38:41]
	v_mfma_f32_16x16x32_bf16 v[66:69], v[138:141], v[170:173], v[66:69]
	v_mfma_f32_16x16x32_bf16 v[62:65], v[146:149], v[170:173], v[62:65]
	v_mfma_f32_16x16x32_bf16 v[58:61], v[138:141], v[178:181], v[58:61]
	v_mfma_f32_16x16x32_bf16 v[54:57], v[146:149], v[178:181], v[54:57]
	v_mfma_f32_16x16x32_bf16 v[50:53], v[138:141], v[186:189], v[50:53]
	v_mfma_f32_16x16x32_bf16 v[46:49], v[146:149], v[186:189], v[46:49]
	v_mfma_f32_16x16x32_bf16 v[42:45], v[138:141], v[226:229], v[42:45]
	v_mfma_f32_16x16x32_bf16 v[38:41], v[146:149], v[226:229], v[38:41]
	s_setprio 0
	s_setprio 1
	v_mfma_f32_16x16x32_bf16 v[34:37], v[150:153], v[166:169], v[34:37]
	s_add_i32 s73, s73, 2
	v_mfma_f32_16x16x32_bf16 v[30:33], v[158:161], v[166:169], v[30:33]
	s_add_u32 s6, s6, 0x100
	v_mfma_f32_16x16x32_bf16 v[26:29], v[150:153], v[174:177], v[26:29]
	s_addc_u32 s7, s7, 0
	v_mfma_f32_16x16x32_bf16 v[22:25], v[158:161], v[174:177], v[22:25]
	s_add_u32 s71, s71, 0x100
	v_mfma_f32_16x16x32_bf16 v[18:21], v[150:153], v[182:185], v[18:21]
	s_addc_u32 s72, s72, 0
	v_mfma_f32_16x16x32_bf16 v[14:17], v[158:161], v[182:185], v[14:17]
	s_cmp_gt_u32 s73, 13
	v_mfma_f32_16x16x32_bf16 v[8:11], v[150:153], v[190:193], v[10:13]
	v_mfma_f32_16x16x32_bf16 v[4:7], v[158:161], v[190:193], v[4:7]
	v_mfma_f32_16x16x32_bf16 v[34:37], v[154:157], v[170:173], v[34:37]
	v_mfma_f32_16x16x32_bf16 v[30:33], v[162:165], v[170:173], v[30:33]
	v_mfma_f32_16x16x32_bf16 v[26:29], v[154:157], v[178:181], v[26:29]
	v_mfma_f32_16x16x32_bf16 v[22:25], v[162:165], v[178:181], v[22:25]
	v_mfma_f32_16x16x32_bf16 v[18:21], v[154:157], v[186:189], v[18:21]
	v_mfma_f32_16x16x32_bf16 v[14:17], v[162:165], v[186:189], v[14:17]
	v_mfma_f32_16x16x32_bf16 v[10:13], v[154:157], v[226:229], v[8:11]
	v_mfma_f32_16x16x32_bf16 v[6:9], v[162:165], v[226:229], v[4:7]
	s_setprio 0
	s_barrier
	s_cbranch_scc0 .LBB0_2105
	s_and_b64 vcc, exec, s[24:25]
	s_cbranch_vccz .LBB0_2108
	s_barrier

; #define PG8_STAGE(bufoff, gbase, voff) do { _Pragma("unroll") for (int _i = 0; _i < 2; ++_i) \
;         __builtin_amdgcn_global_load_lds((const unsigned*)((const char*)(gbase) + (voff)[_i]), (PG8_LAS unsigned*)(lds + (bufoff) + ldsw + _i * 8192), 16, 0, 0); } while (0)
; #define PG8_LDA(dst, b, h) do { _Pragma("unroll") for (int m = 0; m < 4; ++m) _Pragma("unroll") for (int k = 0; k < 2; ++k) dst[m][k] = *(const PG8_LAS bf16x8*)(lds + PG8_SA(b, h) + aoff + m * 2048 + k * 1024); } while (0)
; #define PG8_LDB(dst, b, h) do { _Pragma("unroll") for (int n = 0; n < 2; ++n) _Pragma("unroll") for (int k = 0; k < 2; ++k) dst[n][k] = *(const PG8_LAS bf16x8*)(lds + PG8_SB(b, h) + boff + n * 2048 + k * 1024); } while (0)
; #define PG8_MMA(ai, bj, At, Bt) do { __builtin_amdgcn_s_setprio(1); _Pragma("unroll") for (int m = 0; m < 4; ++m) _Pragma("unroll") for (int n = 0; n < 2; ++n) _Pragma("unroll") for (int k = 0; k < 2; ++k) \
;         acc[ai][bj][m][n] = __builtin_amdgcn_mfma_f32_16x16x32_bf16(Bt[n][k], At[m][k], acc[ai][bj][m][n], 0, 0, 0); __builtin_amdgcn_s_setprio(0); } while (0)
; #define PG8_WAIT_V(n) asm volatile("s_waitcnt vmcnt(" #n ")" ::: "memory")
; #define PG8_WAIT_L(n) asm volatile("s_waitcnt lgkmcnt(" #n ")" ::: "memory")
; #define PG8_BAR __builtin_amdgcn_s_barrier()
; #define PG8_SCHED __builtin_amdgcn_sched_barrier(0)
; template <class Epi, bool ALIGN_EPI, bool ABLK = false>
; __device__ __forceinline__ void gemm_phase(PG8_LAS unsigned char* lds, const Gemm g, const StaticOrder& S, const Epi& E) {
;     ...
;             const char* a1 = cA + (size_t)(t + 1) * kstepA;
;             const char* a2 = last ? nA : cA + (size_t)(t + 2) * kstepA; const char* b2 = last ? nB : cB + (size_t)(t + 2) * kstepB;
;             const char* a3 = a2 + kstepA; const char* b3 = b2 + kstepB;
;             PG8_LDB(B0, 0, 0); PG8_LDB(B1, 0, 1); PG8_SCHED; PG8_LDA(At, 0, 0); PG8_STAGE(PG8_SA(1, 1), a1 + hstepA, voffA);
;             PG8_WAIT_V(8); PG8_WAIT_L(0); PG8_BAR; PG8_MMA(0, 0, At, B0); PG8_MMA(0, 1, At, B1); PG8_BAR; PG8_SCHED;
;             PG8_LDA(At, 0, 1); PG8_STAGE(PG8_SB(0, 0), b2, voffB); PG8_STAGE(PG8_SB(0, 1), b2 + hstepB, voffB); PG8_STAGE(PG8_SA(0, 0), a2, voffA);
.LBB0_2289:
	ds_read_b128 v[102:105], v232
	ds_read_b128 v[110:113], v232 offset:1024
	ds_read_b128 v[122:125], v232 offset:2048
	ds_read_b128 v[134:137], v232 offset:3072
	ds_read_b128 v[146:149], v233
	ds_read_b128 v[150:153], v233 offset:1024
	ds_read_b128 v[154:157], v233 offset:2048
	ds_read_b128 v[158:161], v233 offset:3072
	s_cmp_eq_u32 s82, 12
	s_cselect_b32 s85, s51, s57
	s_cselect_b32 s84, s60, s56
	s_cselect_b32 s59, s49, s81
	s_cselect_b32 s58, s61, s80
	s_movk_i32 s86, 0xc000
	v_lshl_add_u64 v[212:213], s[56:57], 0, v[186:187]
	s_mov_b32 s87, -1
	v_lshl_add_u64 v[244:245], v[212:213], 0, s[86:87]
	s_movk_i32 s86, 0xe000
	s_add_i32 m0, s9, 0xc000
	s_mov_b32 s87, -1
	ds_read_b128 v[162:165], v234
	ds_read_b128 v[166:169], v234 offset:1024
	ds_read_b128 v[170:173], v234 offset:2048
	ds_read_b128 v[174:177], v234 offset:3072
	ds_read_b128 v[178:181], v234 offset:4096
	ds_read_b128 v[182:185], v234 offset:5120
	ds_read_b128 v[236:239], v234 offset:6144
	ds_read_b128 v[240:243], v234 offset:7168
	global_load_lds_dwordx4 v[244:245], off
	v_lshl_add_u64 v[212:213], v[212:213], 0, s[86:87]
	s_add_i32 m0, s9, 0xe000
	s_nop 0
	global_load_lds_dwordx4 v[212:213], off
	s_waitcnt vmcnt(8)
	s_waitcnt lgkmcnt(0)
	s_barrier
	s_setprio 1
	s_waitcnt lgkmcnt(0)
	v_mfma_f32_16x16x32_bf16 v[142:145], v[102:105], v[162:165], v[142:145]
	v_mfma_f32_16x16x32_bf16 v[138:141], v[122:125], v[162:165], v[138:141]
	v_mfma_f32_16x16x32_bf16 v[118:121], v[102:105], v[170:173], v[118:121]
	v_mfma_f32_16x16x32_bf16 v[114:117], v[122:125], v[170:173], v[114:117]
	v_mfma_f32_16x16x32_bf16 v[94:97], v[102:105], v[178:181], v[94:97]
	v_mfma_f32_16x16x32_bf16 v[90:93], v[122:125], v[178:181], v[90:93]
	v_mfma_f32_16x16x32_bf16 v[78:81], v[102:105], v[236:239], v[78:81]
	v_mfma_f32_16x16x32_bf16 v[74:77], v[122:125], v[236:239], v[74:77]
	v_mfma_f32_16x16x32_bf16 v[142:145], v[110:113], v[166:169], v[142:145]
	v_mfma_f32_16x16x32_bf16 v[138:141], v[134:137], v[166:169], v[138:141]
	v_mfma_f32_16x16x32_bf16 v[118:121], v[110:113], v[174:177], v[118:121]
	v_mfma_f32_16x16x32_bf16 v[114:117], v[134:137], v[174:177], v[114:117]
	v_mfma_f32_16x16x32_bf16 v[94:97], v[110:113], v[182:185], v[94:97]
	v_mfma_f32_16x16x32_bf16 v[90:93], v[134:137], v[182:185], v[90:93]
	v_mfma_f32_16x16x32_bf16 v[78:81], v[110:113], v[240:243], v[78:81]
	v_mfma_f32_16x16x32_bf16 v[74:77], v[134:137], v[240:243], v[74:77]
	s_setprio 0
	s_setprio 1
	v_mfma_f32_16x16x32_bf16 v[130:133], v[146:149], v[162:165], v[130:133]
	s_add_i32 s83, s77, s65
	v_mfma_f32_16x16x32_bf16 v[126:129], v[154:157], v[162:165], v[126:129]
	s_mov_b32 m0, s83
	v_mfma_f32_16x16x32_bf16 v[106:109], v[146:149], v[170:173], v[106:109]
	v_mfma_f32_16x16x32_bf16 v[98:101], v[154:157], v[170:173], v[98:101]
	v_mfma_f32_16x16x32_bf16 v[86:89], v[146:149], v[178:181], v[86:89]
	v_mfma_f32_16x16x32_bf16 v[82:85], v[154:157], v[178:181], v[82:85]
	v_mfma_f32_16x16x32_bf16 v[70:73], v[146:149], v[236:239], v[70:73]
	v_mfma_f32_16x16x32_bf16 v[66:69], v[154:157], v[236:239], v[66:69]
	v_mfma_f32_16x16x32_bf16 v[130:133], v[150:153], v[166:169], v[130:133]
	v_mfma_f32_16x16x32_bf16 v[126:129], v[158:161], v[166:169], v[126:129]
	v_mfma_f32_16x16x32_bf16 v[106:109], v[150:153], v[174:177], v[106:109]
	v_lshl_add_u64 v[212:213], s[58:59], 0, v[188:189]
	v_mfma_f32_16x16x32_bf16 v[98:101], v[158:161], v[174:177], v[98:101]
	v_mfma_f32_16x16x32_bf16 v[86:89], v[150:153], v[182:185], v[86:89]
	v_mfma_f32_16x16x32_bf16 v[82:85], v[158:161], v[182:185], v[82:85]
	v_mfma_f32_16x16x32_bf16 v[70:73], v[150:153], v[240:243], v[70:73]
	v_mfma_f32_16x16x32_bf16 v[66:69], v[158:161], v[240:243], v[66:69]
	s_setprio 0
	s_barrier
	ds_read_b128 v[162:165], v234 offset:16384
	ds_read_b128 v[166:169], v234 offset:17408
	ds_read_b128 v[170:173], v234 offset:18432
	ds_read_b128 v[174:177], v234 offset:19456
	ds_read_b128 v[178:181], v234 offset:20480
	ds_read_b128 v[182:185], v234 offset:21504
	ds_read_b128 v[236:239], v234 offset:22528
	ds_read_b128 v[240:243], v234 offset:23552
	global_load_lds_dwordx4 v[212:213], off
	s_add_i32 m0, s83, 0x2000
	s_add_u32 s86, s58, 0x40000
	v_lshl_add_u64 v[244:245], s[58:59], 0, v[190:191]
	s_addc_u32 s87, s59, 0
	s_add_i32 s83, s78, s65
	global_load_lds_dwordx4 v[244:245], off
	v_lshl_add_u64 v[246:247], s[86:87], 0, v[188:189]
	s_mov_b32 m0, s83
	s_nop 0
	global_load_lds_dwordx4 v[246:247], off
	v_lshl_add_u64 v[246:247], s[86:87], 0, v[190:191]
	s_add_i32 m0, s83, 0x2000
	s_nop 0
	global_load_lds_dwordx4 v[246:247], off
	v_lshl_add_u64 v[246:247], s[84:85], 0, v[186:187]
	s_mov_b32 m0, s9
	v_lshl_add_u64 v[248:249], v[246:247], 0, s[10:11]
	global_load_lds_dwordx4 v[246:247], off
	s_mov_b32 m0, s66
	s_nop 0
	global_load_lds_dwordx4 v[248:249], off
	s_waitcnt vmcnt(8)
	s_waitcnt lgkmcnt(0)
	s_barrier
; #define PG8_STAGE(bufoff, gbase, voff) do { _Pragma("unroll") for (int _i = 0; _i < 2; ++_i) \
;         __builtin_amdgcn_global_load_lds((const unsigned*)((const char*)(gbase) + (voff)[_i]), (PG8_LAS unsigned*)(lds + (bufoff) + ldsw + _i * 8192), 16, 0, 0); } while (0)
; #define PG8_LDA(dst, b, h) do { _Pragma("unroll") for (int m = 0; m < 4; ++m) _Pragma("unroll") for (int k = 0; k < 2; ++k) dst[m][k] = *(const PG8_LAS bf16x8*)(lds + PG8_SA(b, h) + aoff + m * 2048 + k * 1024); } while (0)
; #define PG8_LDB(dst, b, h) do { _Pragma("unroll") for (int n = 0; n < 2; ++n) _Pragma("unroll") for (int k = 0; k < 2; ++k) dst[n][k] = *(const PG8_LAS bf16x8*)(lds + PG8_SB(b, h) + boff + n * 2048 + k * 1024); } while (0)
; #define PG8_MMA(ai, bj, At, Bt) do { __builtin_amdgcn_s_setprio(1); _Pragma("unroll") for (int m = 0; m < 4; ++m) _Pragma("unroll") for (int n = 0; n < 2; ++n) _Pragma("unroll") for (int k = 0; k < 2; ++k) \
;         acc[ai][bj][m][n] = __builtin_amdgcn_mfma_f32_16x16x32_bf16(Bt[n][k], At[m][k], acc[ai][bj][m][n], 0, 0, 0); __builtin_amdgcn_s_setprio(0); } while (0)
; #define PG8_WAIT_V(n) asm volatile("s_waitcnt vmcnt(" #n ")" ::: "memory")
; #define PG8_WAIT_L(n) asm volatile("s_waitcnt lgkmcnt(" #n ")" ::: "memory")
; #define PG8_BAR __builtin_amdgcn_s_barrier()
; #define PG8_SCHED __builtin_amdgcn_sched_barrier(0)
; template <class Epi, bool ALIGN_EPI, bool ABLK = false>
; __device__ __forceinline__ void gemm_phase(PG8_LAS unsigned char* lds, const Gemm g, const StaticOrder& S, const Epi& E) {
;     ...
;             PG8_WAIT_V(8); PG8_WAIT_L(0); PG8_BAR; PG8_MMA(1, 0, At, B0); PG8_MMA(1, 1, At, B1); PG8_BAR; PG8_SCHED;
;             PG8_LDB(B0, 1, 0); PG8_LDB(B1, 1, 1); PG8_SCHED; PG8_LDA(At, 1, 0); PG8_STAGE(PG8_SA(0, 1), a2 + hstepA, voffA);
;             PG8_WAIT_V(8); PG8_WAIT_L(0); PG8_BAR; PG8_MMA(0, 0, At, B0); PG8_MMA(0, 1, At, B1); PG8_BAR; PG8_SCHED;
	s_setprio 1
	s_waitcnt lgkmcnt(0)
	v_mfma_f32_16x16x32_bf16 v[62:65], v[102:105], v[162:165], v[62:65]
	v_mfma_f32_16x16x32_bf16 v[58:61], v[122:125], v[162:165], v[58:61]
	v_mfma_f32_16x16x32_bf16 v[46:49], v[102:105], v[170:173], v[46:49]
	v_mfma_f32_16x16x32_bf16 v[42:45], v[122:125], v[170:173], v[42:45]
	v_mfma_f32_16x16x32_bf16 v[30:33], v[102:105], v[178:181], v[30:33]
	v_mfma_f32_16x16x32_bf16 v[26:29], v[122:125], v[178:181], v[26:29]
	v_mfma_f32_16x16x32_bf16 v[14:17], v[102:105], v[236:239], v[14:17]
	v_mfma_f32_16x16x32_bf16 v[10:13], v[122:125], v[236:239], v[10:13]
	v_mfma_f32_16x16x32_bf16 v[62:65], v[110:113], v[166:169], v[62:65]
	v_mfma_f32_16x16x32_bf16 v[58:61], v[134:137], v[166:169], v[58:61]
	v_mfma_f32_16x16x32_bf16 v[46:49], v[110:113], v[174:177], v[46:49]
	v_mfma_f32_16x16x32_bf16 v[42:45], v[134:137], v[174:177], v[42:45]
	v_mfma_f32_16x16x32_bf16 v[30:33], v[110:113], v[182:185], v[30:33]
	v_mfma_f32_16x16x32_bf16 v[26:29], v[134:137], v[182:185], v[26:29]
	v_mfma_f32_16x16x32_bf16 v[14:17], v[110:113], v[240:243], v[14:17]
	v_mfma_f32_16x16x32_bf16 v[10:13], v[134:137], v[240:243], v[10:13]
	s_setprio 0
	s_setprio 1
	v_mfma_f32_16x16x32_bf16 v[54:57], v[146:149], v[162:165], v[54:57]
	s_add_i32 s83, 0, 0x18000
	v_mfma_f32_16x16x32_bf16 v[50:53], v[154:157], v[162:165], v[50:53]
	s_add_i32 s84, 0, 0x1c000
	v_mfma_f32_16x16x32_bf16 v[38:41], v[146:149], v[170:173], v[38:41]
	v_mfma_f32_16x16x32_bf16 v[34:37], v[154:157], v[170:173], v[34:37]
	v_mfma_f32_16x16x32_bf16 v[22:25], v[146:149], v[178:181], v[22:25]
	v_mfma_f32_16x16x32_bf16 v[18:21], v[154:157], v[178:181], v[18:21]
	v_mfma_f32_16x16x32_bf16 v[6:9], v[146:149], v[236:239], v[6:9]
	v_mfma_f32_16x16x32_bf16 v[2:5], v[154:157], v[236:239], v[2:5]
	v_mfma_f32_16x16x32_bf16 v[54:57], v[150:153], v[166:169], v[54:57]
	v_mfma_f32_16x16x32_bf16 v[50:53], v[158:161], v[166:169], v[50:53]
	v_mfma_f32_16x16x32_bf16 v[38:41], v[150:153], v[174:177], v[38:41]
	v_mfma_f32_16x16x32_bf16 v[34:37], v[158:161], v[174:177], v[34:37]
	v_mfma_f32_16x16x32_bf16 v[22:25], v[150:153], v[182:185], v[22:25]
	v_mfma_f32_16x16x32_bf16 v[18:21], v[158:161], v[182:185], v[18:21]
	v_mfma_f32_16x16x32_bf16 v[6:9], v[150:153], v[240:243], v[6:9]
	v_mfma_f32_16x16x32_bf16 v[2:5], v[158:161], v[240:243], v[2:5]
	s_setprio 0
	s_barrier
	v_add_u32_e32 v134, s83, v224
	v_add_u32_e32 v158, s84, v224
	ds_read_b128 v[102:105], v134
	ds_read_b128 v[110:113], v134 offset:1024
	ds_read_b128 v[122:125], v134 offset:2048
	ds_read_b128 v[134:137], v134 offset:3072
	ds_read_b128 v[146:149], v158
	ds_read_b128 v[150:153], v158 offset:1024
	ds_read_b128 v[154:157], v158 offset:2048
	ds_read_b128 v[158:161], v158 offset:3072
	s_mov_b32 m0, s67
	v_lshl_add_u64 v[248:249], v[246:247], 0, s[12:13]
	ds_read_b128 v[162:165], v234 offset:32768
	ds_read_b128 v[166:169], v234 offset:33792
	ds_read_b128 v[170:173], v234 offset:34816
	ds_read_b128 v[174:177], v234 offset:35840
	ds_read_b128 v[178:181], v234 offset:36864
	ds_read_b128 v[182:185], v234 offset:37888
	ds_read_b128 v[236:239], v234 offset:38912
	ds_read_b128 v[240:243], v234 offset:39936
	global_load_lds_dwordx4 v[248:249], off
	v_lshl_add_u64 v[248:249], v[246:247], 0, s[24:25]
	s_mov_b32 m0, s68
	s_nop 0
	global_load_lds_dwordx4 v[248:249], off
	s_waitcnt vmcnt(8)
	s_waitcnt lgkmcnt(0)
	s_barrier
	s_setprio 1
	s_waitcnt lgkmcnt(0)
	v_mfma_f32_16x16x32_bf16 v[142:145], v[102:105], v[162:165], v[142:145]
	v_mfma_f32_16x16x32_bf16 v[138:141], v[122:125], v[162:165], v[138:141]
	v_mfma_f32_16x16x32_bf16 v[118:121], v[102:105], v[170:173], v[118:121]
	v_mfma_f32_16x16x32_bf16 v[114:117], v[122:125], v[170:173], v[114:117]
	v_mfma_f32_16x16x32_bf16 v[94:97], v[102:105], v[178:181], v[94:97]
	v_mfma_f32_16x16x32_bf16 v[90:93], v[122:125], v[178:181], v[90:93]
	v_mfma_f32_16x16x32_bf16 v[78:81], v[102:105], v[236:239], v[78:81]
	v_mfma_f32_16x16x32_bf16 v[74:77], v[122:125], v[236:239], v[74:77]
	v_mfma_f32_16x16x32_bf16 v[142:145], v[110:113], v[166:169], v[142:145]
	v_mfma_f32_16x16x32_bf16 v[138:141], v[134:137], v[166:169], v[138:141]
	v_mfma_f32_16x16x32_bf16 v[118:121], v[110:113], v[174:177], v[118:121]
	v_mfma_f32_16x16x32_bf16 v[114:117], v[134:137], v[174:177], v[114:117]
	v_mfma_f32_16x16x32_bf16 v[94:97], v[110:113], v[182:185], v[94:97]
	v_mfma_f32_16x16x32_bf16 v[90:93], v[134:137], v[182:185], v[90:93]
	v_mfma_f32_16x16x32_bf16 v[78:81], v[110:113], v[240:243], v[78:81]
	v_mfma_f32_16x16x32_bf16 v[74:77], v[134:137], v[240:243], v[74:77]
	s_setprio 0
	s_setprio 1
	v_mfma_f32_16x16x32_bf16 v[130:133], v[146:149], v[162:165], v[130:133]
	s_add_i32 s83, s83, s65
	v_mfma_f32_16x16x32_bf16 v[126:129], v[154:157], v[162:165], v[126:129]
	s_mov_b32 m0, s83
	v_mfma_f32_16x16x32_bf16 v[106:109], v[146:149], v[170:173], v[106:109]
	v_mfma_f32_16x16x32_bf16 v[98:101], v[154:157], v[170:173], v[98:101]
	v_mfma_f32_16x16x32_bf16 v[86:89], v[146:149], v[178:181], v[86:89]
	v_mfma_f32_16x16x32_bf16 v[82:85], v[154:157], v[178:181], v[82:85]
	v_mfma_f32_16x16x32_bf16 v[70:73], v[146:149], v[236:239], v[70:73]
	v_mfma_f32_16x16x32_bf16 v[66:69], v[154:157], v[236:239], v[66:69]
	v_mfma_f32_16x16x32_bf16 v[130:133], v[150:153], v[166:169], v[130:133]
	v_mfma_f32_16x16x32_bf16 v[126:129], v[158:161], v[166:169], v[126:129]
	v_mfma_f32_16x16x32_bf16 v[106:109], v[150:153], v[174:177], v[106:109]
	v_lshl_add_u64 v[212:213], v[212:213], 0, s[34:35]
	v_mfma_f32_16x16x32_bf16 v[98:101], v[158:161], v[174:177], v[98:101]
	v_mfma_f32_16x16x32_bf16 v[86:89], v[150:153], v[182:185], v[86:89]
	v_mfma_f32_16x16x32_bf16 v[82:85], v[158:161], v[182:185], v[82:85]
	v_mfma_f32_16x16x32_bf16 v[70:73], v[150:153], v[240:243], v[70:73]
	v_mfma_f32_16x16x32_bf16 v[66:69], v[158:161], v[240:243], v[66:69]
	s_setprio 0
	s_barrier
; #define PG8_STAGE(bufoff, gbase, voff) do { _Pragma("unroll") for (int _i = 0; _i < 2; ++_i) \
;         __builtin_amdgcn_global_load_lds((const unsigned*)((const char*)(gbase) + (voff)[_i]), (PG8_LAS unsigned*)(lds + (bufoff) + ldsw + _i * 8192), 16, 0, 0); } while (0)
; #define PG8_LDA(dst, b, h) do { _Pragma("unroll") for (int m = 0; m < 4; ++m) _Pragma("unroll") for (int k = 0; k < 2; ++k) dst[m][k] = *(const PG8_LAS bf16x8*)(lds + PG8_SA(b, h) + aoff + m * 2048 + k * 1024); } while (0)
; #define PG8_MMA(ai, bj, At, Bt) do { __builtin_amdgcn_s_setprio(1); _Pragma("unroll") for (int m = 0; m < 4; ++m) _Pragma("unroll") for (int n = 0; n < 2; ++n) _Pragma("unroll") for (int k = 0; k < 2; ++k) \
;         acc[ai][bj][m][n] = __builtin_amdgcn_mfma_f32_16x16x32_bf16(Bt[n][k], At[m][k], acc[ai][bj][m][n], 0, 0, 0); __builtin_amdgcn_s_setprio(0); } while (0)
; #define PG8_WAIT_V(n) asm volatile("s_waitcnt vmcnt(" #n ")" ::: "memory")
; #define PG8_WAIT_L(n) asm volatile("s_waitcnt lgkmcnt(" #n ")" ::: "memory")
; #define PG8_BAR __builtin_amdgcn_s_barrier()
; #define PG8_SCHED __builtin_amdgcn_sched_barrier(0)
; template <class Epi, bool ALIGN_EPI, bool ABLK = false>
; __device__ __forceinline__ void gemm_phase(PG8_LAS unsigned char* lds, const Gemm g, const StaticOrder& S, const Epi& E) {
;     ...
;             PG8_LDA(At, 1, 1); PG8_STAGE(PG8_SB(1, 0), b3, voffB); PG8_STAGE(PG8_SB(1, 1), b3 + hstepB, voffB); PG8_STAGE(PG8_SA(1, 0), a3, voffA);
;             PG8_WAIT_V(8); PG8_WAIT_L(0); PG8_BAR; PG8_MMA(1, 0, At, B0); PG8_MMA(1, 1, At, B1); PG8_BAR; PG8_SCHED;
;         }
	ds_read_b128 v[162:165], v234 offset:49152
	ds_read_b128 v[166:169], v234 offset:50176
	ds_read_b128 v[170:173], v234 offset:51200
	ds_read_b128 v[174:177], v234 offset:52224
	ds_read_b128 v[178:181], v234 offset:53248
	ds_read_b128 v[182:185], v234 offset:54272
	ds_read_b128 v[236:239], v234 offset:55296
	ds_read_b128 v[240:243], v234 offset:56320
	global_load_lds_dwordx4 v[212:213], off
	s_add_i32 m0, s83, 0x2000
	s_add_u32 s58, s58, 0x40080
	v_lshl_add_u64 v[212:213], v[244:245], 0, s[34:35]
	s_addc_u32 s59, s59, 0
	s_add_i32 s83, s84, s65
	global_load_lds_dwordx4 v[212:213], off
	v_lshl_add_u64 v[212:213], s[58:59], 0, v[188:189]
	s_mov_b32 m0, s83
	s_nop 0
	global_load_lds_dwordx4 v[212:213], off
	v_lshl_add_u64 v[212:213], s[58:59], 0, v[190:191]
	s_add_i32 m0, s83, 0x2000
	s_nop 0
	global_load_lds_dwordx4 v[212:213], off
	v_lshl_add_u64 v[212:213], v[246:247], 0, s[36:37]
	s_mov_b32 m0, s71
	s_nop 0
	global_load_lds_dwordx4 v[212:213], off
	v_lshl_add_u64 v[212:213], v[246:247], 0, s[38:39]
	s_mov_b32 m0, s72
	s_nop 0
	global_load_lds_dwordx4 v[212:213], off
	s_waitcnt vmcnt(8)
	s_waitcnt lgkmcnt(0)
	s_barrier
	s_setprio 1
	s_waitcnt lgkmcnt(0)
	v_mfma_f32_16x16x32_bf16 v[62:65], v[102:105], v[162:165], v[62:65]
	v_mfma_f32_16x16x32_bf16 v[58:61], v[122:125], v[162:165], v[58:61]
	v_mfma_f32_16x16x32_bf16 v[46:49], v[102:105], v[170:173], v[46:49]
	v_mfma_f32_16x16x32_bf16 v[42:45], v[122:125], v[170:173], v[42:45]
	v_mfma_f32_16x16x32_bf16 v[30:33], v[102:105], v[178:181], v[30:33]
	v_mfma_f32_16x16x32_bf16 v[26:29], v[122:125], v[178:181], v[26:29]
	v_mfma_f32_16x16x32_bf16 v[14:17], v[102:105], v[236:239], v[14:17]
	v_mfma_f32_16x16x32_bf16 v[10:13], v[122:125], v[236:239], v[10:13]
	v_mfma_f32_16x16x32_bf16 v[62:65], v[110:113], v[166:169], v[62:65]
	v_mfma_f32_16x16x32_bf16 v[58:61], v[134:137], v[166:169], v[58:61]
	v_mfma_f32_16x16x32_bf16 v[46:49], v[110:113], v[174:177], v[46:49]
	v_mfma_f32_16x16x32_bf16 v[42:45], v[134:137], v[174:177], v[42:45]
	v_mfma_f32_16x16x32_bf16 v[30:33], v[110:113], v[182:185], v[30:33]
	v_mfma_f32_16x16x32_bf16 v[26:29], v[134:137], v[182:185], v[26:29]
	v_mfma_f32_16x16x32_bf16 v[14:17], v[110:113], v[240:243], v[14:17]
	v_mfma_f32_16x16x32_bf16 v[10:13], v[134:137], v[240:243], v[10:13]
	s_setprio 0
	s_setprio 1
	v_mfma_f32_16x16x32_bf16 v[54:57], v[146:149], v[162:165], v[54:57]
	s_add_i32 s82, s82, 2
	v_mfma_f32_16x16x32_bf16 v[50:53], v[154:157], v[162:165], v[50:53]
	s_add_u32 s80, s80, 0x100
	v_mfma_f32_16x16x32_bf16 v[38:41], v[146:149], v[170:173], v[38:41]
	s_addc_u32 s81, s81, 0
	v_mfma_f32_16x16x32_bf16 v[34:37], v[154:157], v[170:173], v[34:37]
	s_add_u32 s56, s56, 0x10000
	v_mfma_f32_16x16x32_bf16 v[22:25], v[146:149], v[178:181], v[22:25]
	s_addc_u32 s57, s57, 0
	v_mfma_f32_16x16x32_bf16 v[18:21], v[154:157], v[178:181], v[18:21]
	s_cmp_gt_u32 s82, 13
	v_mfma_f32_16x16x32_bf16 v[6:9], v[146:149], v[236:239], v[6:9]
	v_mfma_f32_16x16x32_bf16 v[2:5], v[154:157], v[236:239], v[2:5]
	v_mfma_f32_16x16x32_bf16 v[54:57], v[150:153], v[166:169], v[54:57]
	v_mfma_f32_16x16x32_bf16 v[50:53], v[158:161], v[166:169], v[50:53]
	v_mfma_f32_16x16x32_bf16 v[38:41], v[150:153], v[174:177], v[38:41]
	v_mfma_f32_16x16x32_bf16 v[34:37], v[158:161], v[174:177], v[34:37]
	v_mfma_f32_16x16x32_bf16 v[22:25], v[150:153], v[182:185], v[22:25]
	v_mfma_f32_16x16x32_bf16 v[18:21], v[158:161], v[182:185], v[18:21]
	v_mfma_f32_16x16x32_bf16 v[6:9], v[150:153], v[240:243], v[6:9]
	v_mfma_f32_16x16x32_bf16 v[2:5], v[158:161], v[240:243], v[2:5]
	s_setprio 0
	s_barrier
	s_cbranch_scc0 .LBB0_2289
	s_and_b64 vcc, exec, s[40:41]
	s_cbranch_vccz .LBB0_2292
	s_barrier

; #define PG8_STAGE(bufoff, gbase, voff) do { _Pragma("unroll") for (int _i = 0; _i < 2; ++_i) \
;         __builtin_amdgcn_global_load_lds((const unsigned*)((const char*)(gbase) + (voff)[_i]), (PG8_LAS unsigned*)(lds + (bufoff) + ldsw + _i * 8192), 16, 0, 0); } while (0)
; #define PG8_LDA(dst, b, h) do { _Pragma("unroll") for (int m = 0; m < 4; ++m) _Pragma("unroll") for (int k = 0; k < 2; ++k) dst[m][k] = *(const PG8_LAS bf16x8*)(lds + PG8_SA(b, h) + aoff + m * 2048 + k * 1024); } while (0)
; #define PG8_LDB(dst, b, h) do { _Pragma("unroll") for (int n = 0; n < 2; ++n) _Pragma("unroll") for (int k = 0; k < 2; ++k) dst[n][k] = *(const PG8_LAS bf16x8*)(lds + PG8_SB(b, h) + boff + n * 2048 + k * 1024); } while (0)
; #define PG8_MMA(ai, bj, At, Bt) do { __builtin_amdgcn_s_setprio(1); _Pragma("unroll") for (int m = 0; m < 4; ++m) _Pragma("unroll") for (int n = 0; n < 2; ++n) _Pragma("unroll") for (int k = 0; k < 2; ++k) \
;         acc[ai][bj][m][n] = __builtin_amdgcn_mfma_f32_16x16x32_bf16(Bt[n][k], At[m][k], acc[ai][bj][m][n], 0, 0, 0); __builtin_amdgcn_s_setprio(0); } while (0)
; #define PG8_WAIT_V(n) asm volatile("s_waitcnt vmcnt(" #n ")" ::: "memory")
; #define PG8_WAIT_L(n) asm volatile("s_waitcnt lgkmcnt(" #n ")" ::: "memory")
; #define PG8_BAR __builtin_amdgcn_s_barrier()
; #define PG8_SCHED __builtin_amdgcn_sched_barrier(0)
; template <class Epi, bool ALIGN_EPI, bool ABLK = false>
; __device__ __forceinline__ void gemm_phase(PG8_LAS unsigned char* lds, const Gemm g, const StaticOrder& S, const Epi& E) {
;     ...
;             const char* a1 = cA + (size_t)(t + 1) * kstepA;
;             const char* a2 = last ? nA : cA + (size_t)(t + 2) * kstepA; const char* b2 = last ? nB : cB + (size_t)(t + 2) * kstepB;
;             const char* a3 = a2 + kstepA; const char* b3 = b2 + kstepB;
;             PG8_LDB(B0, 0, 0); PG8_LDB(B1, 0, 1); PG8_SCHED; PG8_LDA(At, 0, 0); PG8_STAGE(PG8_SA(1, 1), a1 + hstepA, voffA);
;             PG8_WAIT_V(8); PG8_WAIT_L(0); PG8_BAR; PG8_MMA(0, 0, At, B0); PG8_MMA(0, 1, At, B1); PG8_BAR; PG8_SCHED;
;             PG8_LDA(At, 0, 1); PG8_STAGE(PG8_SB(0, 0), b2, voffB); PG8_STAGE(PG8_SB(0, 1), b2 + hstepB, voffB); PG8_STAGE(PG8_SA(0, 0), a2, voffA);
.LBB0_2631:
	ds_read_b128 v[130:133], v234
	ds_read_b128 v[134:137], v234 offset:1024
	ds_read_b128 v[138:141], v234 offset:2048
	ds_read_b128 v[142:145], v234 offset:3072
	ds_read_b128 v[146:149], v235
	ds_read_b128 v[150:153], v235 offset:1024
	ds_read_b128 v[154:157], v235 offset:2048
	ds_read_b128 v[158:161], v235 offset:3072
	s_cmp_eq_u32 s57, 40
	s_cselect_b32 s81, s13, s53
	s_cselect_b32 s80, s12, s52
	s_cselect_b32 s55, s49, s56
	s_cselect_b32 s54, s48, s51
	v_lshl_add_u64 v[248:249], s[52:53], 0, v[186:187]
	v_lshl_add_u64 v[250:251], v[248:249], 0, s[44:45]
	s_add_i32 m0, s62, 0xc000
	ds_read_b128 v[162:165], v236
	ds_read_b128 v[166:169], v236 offset:1024
	ds_read_b128 v[170:173], v236 offset:2048
	ds_read_b128 v[174:177], v236 offset:3072
	ds_read_b128 v[178:181], v236 offset:4096
	ds_read_b128 v[182:185], v236 offset:5120
	ds_read_b128 v[240:243], v236 offset:6144
	ds_read_b128 v[244:247], v236 offset:7168
	global_load_lds_dwordx4 v[250:251], off
	v_lshl_add_u64 v[248:249], v[248:249], 0, s[46:47]
	s_add_i32 m0, s62, 0xe000
	s_nop 0
	global_load_lds_dwordx4 v[248:249], off
	s_waitcnt vmcnt(8)
	s_waitcnt lgkmcnt(0)
	s_barrier
	s_setprio 1
	s_waitcnt lgkmcnt(0)
	v_mfma_f32_16x16x32_bf16 v[126:129], v[130:133], v[162:165], v[126:129]
	v_mfma_f32_16x16x32_bf16 v[122:125], v[138:141], v[162:165], v[122:125]
	v_mfma_f32_16x16x32_bf16 v[110:113], v[130:133], v[170:173], v[110:113]
	v_mfma_f32_16x16x32_bf16 v[106:109], v[138:141], v[170:173], v[106:109]
	v_mfma_f32_16x16x32_bf16 v[94:97], v[130:133], v[178:181], v[94:97]
	v_mfma_f32_16x16x32_bf16 v[90:93], v[138:141], v[178:181], v[90:93]
	v_mfma_f32_16x16x32_bf16 v[78:81], v[130:133], v[240:243], v[78:81]
	v_mfma_f32_16x16x32_bf16 v[74:77], v[138:141], v[240:243], v[74:77]
	v_mfma_f32_16x16x32_bf16 v[126:129], v[134:137], v[166:169], v[126:129]
	v_mfma_f32_16x16x32_bf16 v[122:125], v[142:145], v[166:169], v[122:125]
	v_mfma_f32_16x16x32_bf16 v[110:113], v[134:137], v[174:177], v[110:113]
	v_mfma_f32_16x16x32_bf16 v[106:109], v[142:145], v[174:177], v[106:109]
	v_mfma_f32_16x16x32_bf16 v[94:97], v[134:137], v[182:185], v[94:97]
	v_mfma_f32_16x16x32_bf16 v[90:93], v[142:145], v[182:185], v[90:93]
	v_mfma_f32_16x16x32_bf16 v[78:81], v[134:137], v[244:247], v[78:81]
	v_mfma_f32_16x16x32_bf16 v[74:77], v[142:145], v[244:247], v[74:77]
	s_setprio 0
	s_setprio 1
	v_mfma_f32_16x16x32_bf16 v[118:121], v[146:149], v[162:165], v[118:121]
	s_add_i32 s79, s74, s61
	v_mfma_f32_16x16x32_bf16 v[114:117], v[154:157], v[162:165], v[114:117]
	s_mov_b32 m0, s79
	v_mfma_f32_16x16x32_bf16 v[102:105], v[146:149], v[170:173], v[102:105]
	v_mfma_f32_16x16x32_bf16 v[98:101], v[154:157], v[170:173], v[98:101]
	v_mfma_f32_16x16x32_bf16 v[86:89], v[146:149], v[178:181], v[86:89]
	v_mfma_f32_16x16x32_bf16 v[82:85], v[154:157], v[178:181], v[82:85]
	v_mfma_f32_16x16x32_bf16 v[70:73], v[146:149], v[240:243], v[70:73]
	v_mfma_f32_16x16x32_bf16 v[66:69], v[154:157], v[240:243], v[66:69]
	v_mfma_f32_16x16x32_bf16 v[118:121], v[150:153], v[166:169], v[118:121]
	v_mfma_f32_16x16x32_bf16 v[114:117], v[158:161], v[166:169], v[114:117]
	v_mfma_f32_16x16x32_bf16 v[102:105], v[150:153], v[174:177], v[102:105]
	v_lshl_add_u64 v[248:249], s[54:55], 0, v[188:189]
	v_mfma_f32_16x16x32_bf16 v[98:101], v[158:161], v[174:177], v[98:101]
	v_mfma_f32_16x16x32_bf16 v[86:89], v[150:153], v[182:185], v[86:89]
	v_mfma_f32_16x16x32_bf16 v[82:85], v[158:161], v[182:185], v[82:85]
	v_mfma_f32_16x16x32_bf16 v[70:73], v[150:153], v[244:247], v[70:73]
	v_mfma_f32_16x16x32_bf16 v[66:69], v[158:161], v[244:247], v[66:69]
	s_setprio 0
	s_barrier
	ds_read_b128 v[162:165], v236 offset:16384
	ds_read_b128 v[166:169], v236 offset:17408
	ds_read_b128 v[170:173], v236 offset:18432
	ds_read_b128 v[174:177], v236 offset:19456
	ds_read_b128 v[178:181], v236 offset:20480
	ds_read_b128 v[182:185], v236 offset:21504
	ds_read_b128 v[240:243], v236 offset:22528
	ds_read_b128 v[244:247], v236 offset:23552
	global_load_lds_dwordx4 v[248:249], off
	s_add_i32 m0, s79, 0x2000
	s_add_u32 s82, s54, 0xb0000
	v_lshl_add_u64 v[250:251], s[54:55], 0, v[190:191]
	s_addc_u32 s83, s55, 0
	s_add_i32 s79, s75, s61
	global_load_lds_dwordx4 v[250:251], off
	v_lshl_add_u64 v[252:253], s[82:83], 0, v[188:189]
	s_mov_b32 m0, s79
	s_nop 0
	global_load_lds_dwordx4 v[252:253], off
	v_lshl_add_u64 v[252:253], s[82:83], 0, v[190:191]
	s_add_i32 m0, s79, 0x2000
	s_nop 0
	global_load_lds_dwordx4 v[252:253], off
	v_lshl_add_u64 v[252:253], s[80:81], 0, v[186:187]
	s_mov_b32 m0, s62
	v_lshl_add_u64 v[208:209], v[252:253], 0, s[22:23]
	global_load_lds_dwordx4 v[252:253], off
	s_mov_b32 m0, s63
	s_nop 0
	global_load_lds_dwordx4 v[208:209], off
	s_waitcnt vmcnt(8)
	s_waitcnt lgkmcnt(0)
	s_barrier
; #define PG8_STAGE(bufoff, gbase, voff) do { _Pragma("unroll") for (int _i = 0; _i < 2; ++_i) \
;         __builtin_amdgcn_global_load_lds((const unsigned*)((const char*)(gbase) + (voff)[_i]), (PG8_LAS unsigned*)(lds + (bufoff) + ldsw + _i * 8192), 16, 0, 0); } while (0)
; #define PG8_LDA(dst, b, h) do { _Pragma("unroll") for (int m = 0; m < 4; ++m) _Pragma("unroll") for (int k = 0; k < 2; ++k) dst[m][k] = *(const PG8_LAS bf16x8*)(lds + PG8_SA(b, h) + aoff + m * 2048 + k * 1024); } while (0)
; #define PG8_LDB(dst, b, h) do { _Pragma("unroll") for (int n = 0; n < 2; ++n) _Pragma("unroll") for (int k = 0; k < 2; ++k) dst[n][k] = *(const PG8_LAS bf16x8*)(lds + PG8_SB(b, h) + boff + n * 2048 + k * 1024); } while (0)
; #define PG8_MMA(ai, bj, At, Bt) do { __builtin_amdgcn_s_setprio(1); _Pragma("unroll") for (int m = 0; m < 4; ++m) _Pragma("unroll") for (int n = 0; n < 2; ++n) _Pragma("unroll") for (int k = 0; k < 2; ++k) \
;         acc[ai][bj][m][n] = __builtin_amdgcn_mfma_f32_16x16x32_bf16(Bt[n][k], At[m][k], acc[ai][bj][m][n], 0, 0, 0); __builtin_amdgcn_s_setprio(0); } while (0)
; #define PG8_WAIT_V(n) asm volatile("s_waitcnt vmcnt(" #n ")" ::: "memory")
; #define PG8_WAIT_L(n) asm volatile("s_waitcnt lgkmcnt(" #n ")" ::: "memory")
; #define PG8_BAR __builtin_amdgcn_s_barrier()
; #define PG8_SCHED __builtin_amdgcn_sched_barrier(0)
; template <class Epi, bool ALIGN_EPI, bool ABLK = false>
; __device__ __forceinline__ void gemm_phase(PG8_LAS unsigned char* lds, const Gemm g, const StaticOrder& S, const Epi& E) {
;     ...
;             PG8_WAIT_V(8); PG8_WAIT_L(0); PG8_BAR; PG8_MMA(1, 0, At, B0); PG8_MMA(1, 1, At, B1); PG8_BAR; PG8_SCHED;
;             PG8_LDB(B0, 1, 0); PG8_LDB(B1, 1, 1); PG8_SCHED; PG8_LDA(At, 1, 0); PG8_STAGE(PG8_SA(0, 1), a2 + hstepA, voffA);
;             PG8_WAIT_V(8); PG8_WAIT_L(0); PG8_BAR; PG8_MMA(0, 0, At, B0); PG8_MMA(0, 1, At, B1); PG8_BAR; PG8_SCHED;
	s_setprio 1
	s_waitcnt lgkmcnt(0)
	v_mfma_f32_16x16x32_bf16 v[62:65], v[130:133], v[162:165], v[62:65]
	v_mfma_f32_16x16x32_bf16 v[58:61], v[138:141], v[162:165], v[58:61]
	v_mfma_f32_16x16x32_bf16 v[46:49], v[130:133], v[170:173], v[46:49]
	v_mfma_f32_16x16x32_bf16 v[42:45], v[138:141], v[170:173], v[42:45]
	v_mfma_f32_16x16x32_bf16 v[30:33], v[130:133], v[178:181], v[30:33]
	v_mfma_f32_16x16x32_bf16 v[26:29], v[138:141], v[178:181], v[26:29]
	v_mfma_f32_16x16x32_bf16 v[14:17], v[130:133], v[240:243], v[14:17]
	v_mfma_f32_16x16x32_bf16 v[10:13], v[138:141], v[240:243], v[10:13]
	v_mfma_f32_16x16x32_bf16 v[62:65], v[134:137], v[166:169], v[62:65]
	v_mfma_f32_16x16x32_bf16 v[58:61], v[142:145], v[166:169], v[58:61]
	v_mfma_f32_16x16x32_bf16 v[46:49], v[134:137], v[174:177], v[46:49]
	v_mfma_f32_16x16x32_bf16 v[42:45], v[142:145], v[174:177], v[42:45]
	v_mfma_f32_16x16x32_bf16 v[30:33], v[134:137], v[182:185], v[30:33]
	v_mfma_f32_16x16x32_bf16 v[26:29], v[142:145], v[182:185], v[26:29]
	v_mfma_f32_16x16x32_bf16 v[14:17], v[134:137], v[244:247], v[14:17]
	v_mfma_f32_16x16x32_bf16 v[10:13], v[142:145], v[244:247], v[10:13]
	s_setprio 0
	s_setprio 1
	v_mfma_f32_16x16x32_bf16 v[54:57], v[146:149], v[162:165], v[54:57]
	s_add_i32 s79, 0, 0x18000
	v_mfma_f32_16x16x32_bf16 v[50:53], v[154:157], v[162:165], v[50:53]
	s_add_i32 s80, 0, 0x1c000
	v_mfma_f32_16x16x32_bf16 v[38:41], v[146:149], v[170:173], v[38:41]
	v_mfma_f32_16x16x32_bf16 v[34:37], v[154:157], v[170:173], v[34:37]
	v_mfma_f32_16x16x32_bf16 v[22:25], v[146:149], v[178:181], v[22:25]
	v_mfma_f32_16x16x32_bf16 v[18:21], v[154:157], v[178:181], v[18:21]
	v_mfma_f32_16x16x32_bf16 v[6:9], v[146:149], v[240:243], v[6:9]
	v_mfma_f32_16x16x32_bf16 v[2:5], v[154:157], v[240:243], v[2:5]
	v_mfma_f32_16x16x32_bf16 v[54:57], v[150:153], v[166:169], v[54:57]
	v_mfma_f32_16x16x32_bf16 v[50:53], v[158:161], v[166:169], v[50:53]
	v_mfma_f32_16x16x32_bf16 v[38:41], v[150:153], v[174:177], v[38:41]
	v_mfma_f32_16x16x32_bf16 v[34:37], v[158:161], v[174:177], v[34:37]
	v_mfma_f32_16x16x32_bf16 v[22:25], v[150:153], v[182:185], v[22:25]
	v_mfma_f32_16x16x32_bf16 v[18:21], v[158:161], v[182:185], v[18:21]
	v_mfma_f32_16x16x32_bf16 v[6:9], v[150:153], v[244:247], v[6:9]
	v_mfma_f32_16x16x32_bf16 v[2:5], v[158:161], v[244:247], v[2:5]
	s_setprio 0
	s_barrier
	v_add_u32_e32 v142, s79, v215
	v_add_u32_e32 v158, s80, v215
	ds_read_b128 v[130:133], v142
	ds_read_b128 v[134:137], v142 offset:1024
	ds_read_b128 v[138:141], v142 offset:2048
	ds_read_b128 v[142:145], v142 offset:3072
	ds_read_b128 v[146:149], v158
	ds_read_b128 v[150:153], v158 offset:1024
	ds_read_b128 v[154:157], v158 offset:2048
	ds_read_b128 v[158:161], v158 offset:3072
	s_mov_b32 m0, s64
	v_lshl_add_u64 v[208:209], v[252:253], 0, s[24:25]
	ds_read_b128 v[162:165], v236 offset:32768
	ds_read_b128 v[166:169], v236 offset:33792
	ds_read_b128 v[170:173], v236 offset:34816
	ds_read_b128 v[174:177], v236 offset:35840
	ds_read_b128 v[178:181], v236 offset:36864
	ds_read_b128 v[182:185], v236 offset:37888
	ds_read_b128 v[240:243], v236 offset:38912
	ds_read_b128 v[244:247], v236 offset:39936
	global_load_lds_dwordx4 v[208:209], off
	v_lshl_add_u64 v[208:209], v[252:253], 0, s[26:27]
	s_mov_b32 m0, s65
	s_nop 0
	global_load_lds_dwordx4 v[208:209], off
	s_waitcnt vmcnt(8)
	s_waitcnt lgkmcnt(0)
	s_barrier
	s_setprio 1
	s_waitcnt lgkmcnt(0)
	v_mfma_f32_16x16x32_bf16 v[126:129], v[130:133], v[162:165], v[126:129]
	v_mfma_f32_16x16x32_bf16 v[122:125], v[138:141], v[162:165], v[122:125]
	v_mfma_f32_16x16x32_bf16 v[110:113], v[130:133], v[170:173], v[110:113]
	v_mfma_f32_16x16x32_bf16 v[106:109], v[138:141], v[170:173], v[106:109]
	v_mfma_f32_16x16x32_bf16 v[94:97], v[130:133], v[178:181], v[94:97]
	v_mfma_f32_16x16x32_bf16 v[90:93], v[138:141], v[178:181], v[90:93]
	v_mfma_f32_16x16x32_bf16 v[78:81], v[130:133], v[240:243], v[78:81]
	v_mfma_f32_16x16x32_bf16 v[74:77], v[138:141], v[240:243], v[74:77]
	v_mfma_f32_16x16x32_bf16 v[126:129], v[134:137], v[166:169], v[126:129]
	v_mfma_f32_16x16x32_bf16 v[122:125], v[142:145], v[166:169], v[122:125]
	v_mfma_f32_16x16x32_bf16 v[110:113], v[134:137], v[174:177], v[110:113]
	v_mfma_f32_16x16x32_bf16 v[106:109], v[142:145], v[174:177], v[106:109]
	v_mfma_f32_16x16x32_bf16 v[94:97], v[134:137], v[182:185], v[94:97]
	v_mfma_f32_16x16x32_bf16 v[90:93], v[142:145], v[182:185], v[90:93]
	v_mfma_f32_16x16x32_bf16 v[78:81], v[134:137], v[244:247], v[78:81]
	v_mfma_f32_16x16x32_bf16 v[74:77], v[142:145], v[244:247], v[74:77]
	s_setprio 0
	s_setprio 1
	v_mfma_f32_16x16x32_bf16 v[118:121], v[146:149], v[162:165], v[118:121]
	s_add_i32 s79, s79, s61
	v_mfma_f32_16x16x32_bf16 v[114:117], v[154:157], v[162:165], v[114:117]
	s_mov_b32 m0, s79
	v_mfma_f32_16x16x32_bf16 v[102:105], v[146:149], v[170:173], v[102:105]
	v_mfma_f32_16x16x32_bf16 v[98:101], v[154:157], v[170:173], v[98:101]
	v_mfma_f32_16x16x32_bf16 v[86:89], v[146:149], v[178:181], v[86:89]
	v_mfma_f32_16x16x32_bf16 v[82:85], v[154:157], v[178:181], v[82:85]
	v_mfma_f32_16x16x32_bf16 v[70:73], v[146:149], v[240:243], v[70:73]
	v_mfma_f32_16x16x32_bf16 v[66:69], v[154:157], v[240:243], v[66:69]
	v_mfma_f32_16x16x32_bf16 v[118:121], v[150:153], v[166:169], v[118:121]
	v_mfma_f32_16x16x32_bf16 v[114:117], v[158:161], v[166:169], v[114:117]
	v_mfma_f32_16x16x32_bf16 v[102:105], v[150:153], v[174:177], v[102:105]
	v_lshl_add_u64 v[208:209], v[248:249], 0, s[34:35]
	v_mfma_f32_16x16x32_bf16 v[98:101], v[158:161], v[174:177], v[98:101]
	v_mfma_f32_16x16x32_bf16 v[86:89], v[150:153], v[182:185], v[86:89]
	v_mfma_f32_16x16x32_bf16 v[82:85], v[158:161], v[182:185], v[82:85]
	v_mfma_f32_16x16x32_bf16 v[70:73], v[150:153], v[244:247], v[70:73]
	v_mfma_f32_16x16x32_bf16 v[66:69], v[158:161], v[244:247], v[66:69]
	s_setprio 0
	s_barrier
; #define PG8_STAGE(bufoff, gbase, voff) do { _Pragma("unroll") for (int _i = 0; _i < 2; ++_i) \
;         __builtin_amdgcn_global_load_lds((const unsigned*)((const char*)(gbase) + (voff)[_i]), (PG8_LAS unsigned*)(lds + (bufoff) + ldsw + _i * 8192), 16, 0, 0); } while (0)
; #define PG8_LDA(dst, b, h) do { _Pragma("unroll") for (int m = 0; m < 4; ++m) _Pragma("unroll") for (int k = 0; k < 2; ++k) dst[m][k] = *(const PG8_LAS bf16x8*)(lds + PG8_SA(b, h) + aoff + m * 2048 + k * 1024); } while (0)
; #define PG8_MMA(ai, bj, At, Bt) do { __builtin_amdgcn_s_setprio(1); _Pragma("unroll") for (int m = 0; m < 4; ++m) _Pragma("unroll") for (int n = 0; n < 2; ++n) _Pragma("unroll") for (int k = 0; k < 2; ++k) \
;         acc[ai][bj][m][n] = __builtin_amdgcn_mfma_f32_16x16x32_bf16(Bt[n][k], At[m][k], acc[ai][bj][m][n], 0, 0, 0); __builtin_amdgcn_s_setprio(0); } while (0)
; #define PG8_WAIT_V(n) asm volatile("s_waitcnt vmcnt(" #n ")" ::: "memory")
; #define PG8_WAIT_L(n) asm volatile("s_waitcnt lgkmcnt(" #n ")" ::: "memory")
; #define PG8_BAR __builtin_amdgcn_s_barrier()
; #define PG8_SCHED __builtin_amdgcn_sched_barrier(0)
; template <class Epi, bool ALIGN_EPI, bool ABLK = false>
; __device__ __forceinline__ void gemm_phase(PG8_LAS unsigned char* lds, const Gemm g, const StaticOrder& S, const Epi& E) {
;     ...
;             PG8_LDA(At, 1, 1); PG8_STAGE(PG8_SB(1, 0), b3, voffB); PG8_STAGE(PG8_SB(1, 1), b3 + hstepB, voffB); PG8_STAGE(PG8_SA(1, 0), a3, voffA);
;             PG8_WAIT_V(8); PG8_WAIT_L(0); PG8_BAR; PG8_MMA(1, 0, At, B0); PG8_MMA(1, 1, At, B1); PG8_BAR; PG8_SCHED;
;         }
	ds_read_b128 v[162:165], v236 offset:49152
	ds_read_b128 v[166:169], v236 offset:50176
	ds_read_b128 v[170:173], v236 offset:51200
	ds_read_b128 v[174:177], v236 offset:52224
	ds_read_b128 v[178:181], v236 offset:53248
	ds_read_b128 v[182:185], v236 offset:54272
	ds_read_b128 v[240:243], v236 offset:55296
	ds_read_b128 v[244:247], v236 offset:56320
	global_load_lds_dwordx4 v[208:209], off
	s_add_i32 m0, s79, 0x2000
	s_add_u32 s54, s54, 0xb0080
	v_lshl_add_u64 v[208:209], v[250:251], 0, s[34:35]
	s_addc_u32 s55, s55, 0
	s_add_i32 s79, s80, s61
	global_load_lds_dwordx4 v[208:209], off
	v_lshl_add_u64 v[208:209], s[54:55], 0, v[188:189]
	s_mov_b32 m0, s79
	s_nop 0
	global_load_lds_dwordx4 v[208:209], off
	v_lshl_add_u64 v[208:209], s[54:55], 0, v[190:191]
	s_add_i32 m0, s79, 0x2000
	s_nop 0
	global_load_lds_dwordx4 v[208:209], off
	v_lshl_add_u64 v[208:209], v[252:253], 0, s[36:37]
	s_mov_b32 m0, s69
	s_nop 0
	global_load_lds_dwordx4 v[208:209], off
	v_lshl_add_u64 v[208:209], v[252:253], 0, s[38:39]
	s_mov_b32 m0, s70
	s_nop 0
	global_load_lds_dwordx4 v[208:209], off
	s_waitcnt vmcnt(8)
	s_waitcnt lgkmcnt(0)
	s_barrier
	s_setprio 1
	s_waitcnt lgkmcnt(0)
	v_mfma_f32_16x16x32_bf16 v[62:65], v[130:133], v[162:165], v[62:65]
	v_mfma_f32_16x16x32_bf16 v[58:61], v[138:141], v[162:165], v[58:61]
	v_mfma_f32_16x16x32_bf16 v[46:49], v[130:133], v[170:173], v[46:49]
	v_mfma_f32_16x16x32_bf16 v[42:45], v[138:141], v[170:173], v[42:45]
	v_mfma_f32_16x16x32_bf16 v[30:33], v[130:133], v[178:181], v[30:33]
	v_mfma_f32_16x16x32_bf16 v[26:29], v[138:141], v[178:181], v[26:29]
	v_mfma_f32_16x16x32_bf16 v[14:17], v[130:133], v[240:243], v[14:17]
	v_mfma_f32_16x16x32_bf16 v[10:13], v[138:141], v[240:243], v[10:13]
	v_mfma_f32_16x16x32_bf16 v[62:65], v[134:137], v[166:169], v[62:65]
	v_mfma_f32_16x16x32_bf16 v[58:61], v[142:145], v[166:169], v[58:61]
	v_mfma_f32_16x16x32_bf16 v[46:49], v[134:137], v[174:177], v[46:49]
	v_mfma_f32_16x16x32_bf16 v[42:45], v[142:145], v[174:177], v[42:45]
	v_mfma_f32_16x16x32_bf16 v[30:33], v[134:137], v[182:185], v[30:33]
	v_mfma_f32_16x16x32_bf16 v[26:29], v[142:145], v[182:185], v[26:29]
	v_mfma_f32_16x16x32_bf16 v[14:17], v[134:137], v[244:247], v[14:17]
	v_mfma_f32_16x16x32_bf16 v[10:13], v[142:145], v[244:247], v[10:13]
	s_setprio 0
	s_setprio 1
	v_mfma_f32_16x16x32_bf16 v[54:57], v[146:149], v[162:165], v[54:57]
	s_add_i32 s57, s57, 2
	v_mfma_f32_16x16x32_bf16 v[50:53], v[154:157], v[162:165], v[50:53]
	s_add_u32 s51, s51, 0x100
	v_mfma_f32_16x16x32_bf16 v[38:41], v[146:149], v[170:173], v[38:41]
	s_addc_u32 s56, s56, 0
	v_mfma_f32_16x16x32_bf16 v[34:37], v[154:157], v[170:173], v[34:37]
	s_add_u32 s52, s52, 0x10000
	v_mfma_f32_16x16x32_bf16 v[22:25], v[146:149], v[178:181], v[22:25]
	s_addc_u32 s53, s53, 0
	v_mfma_f32_16x16x32_bf16 v[18:21], v[154:157], v[178:181], v[18:21]
	s_cmp_gt_u32 s57, 41
	v_mfma_f32_16x16x32_bf16 v[6:9], v[146:149], v[240:243], v[6:9]
	v_mfma_f32_16x16x32_bf16 v[2:5], v[154:157], v[240:243], v[2:5]
	v_mfma_f32_16x16x32_bf16 v[54:57], v[150:153], v[166:169], v[54:57]
	v_mfma_f32_16x16x32_bf16 v[50:53], v[158:161], v[166:169], v[50:53]
	v_mfma_f32_16x16x32_bf16 v[38:41], v[150:153], v[174:177], v[38:41]
	v_mfma_f32_16x16x32_bf16 v[34:37], v[158:161], v[174:177], v[34:37]
	v_mfma_f32_16x16x32_bf16 v[22:25], v[150:153], v[182:185], v[22:25]
	v_mfma_f32_16x16x32_bf16 v[18:21], v[158:161], v[182:185], v[18:21]
	v_mfma_f32_16x16x32_bf16 v[6:9], v[150:153], v[244:247], v[6:9]
	v_mfma_f32_16x16x32_bf16 v[2:5], v[158:161], v[244:247], v[2:5]
	s_setprio 0
	s_barrier
	s_cbranch_scc0 .LBB0_2631
	s_and_b64 vcc, exec, s[40:41]
	s_cbranch_vccz .LBB0_2634
	s_barrier
